# ADIFF item epilogue: groups 1-15 of both rounds hand-scheduled - all z/g loads issued at once into dead registers (rolling slot reuse), exact counted vmcnt per group instead of 30 serialized vmcnt(1)/
# speedup vs baseline: 1.0119x; 1.0046x over previous
; #define LAS __attribute__((address_space(3)))
; __device__ __forceinline__ float xsum32(float v) { const auto r = __builtin_amdgcn_permlane32_swap(__float_as_uint(v), __float_as_uint(v), false, false); return __uint_as_float(r[0]) + __uint_as_float(r[1]); }
; __device__ __forceinline__ void diff_attn_phase(const Params& p, LAS unsigned char* lds) {
;     ...
;             __builtin_amdgcn_s_barrier(); asm volatile("" ::: "memory");
;             LAS float* ex = (LAS float*)lds + wq * 4096 + lne;
;             const float lt = xsum32(l[r]);
;             if (comp == 1) {
;                 const float sc = lam / lt;
; #pragma unroll
;                 for (int t = 0; t < 4; ++t)
; #pragma unroll
;                     for (int i = 0; i < 16; ++i) ex[(t * 16 + i) * 64] = O[r][t][i] * sc;
;             }
;             asm volatile("s_waitcnt lgkmcnt(0)" ::: "memory"); __builtin_amdgcn_s_barrier(); asm volatile("" ::: "memory");
;             if (comp == 0) {
;                 const float i0 = 1.0f / lt; float ss = 0.f;
; #pragma unroll
;                 for (int t = 0; t < 4; ++t)
; #pragma unroll
;                     for (int i = 0; i < 16; ++i) { const float a = O[r][t][i] * i0 - ex[(t * 16 + i) * 64]; O[r][t][i] = a; ss += a * a; if (i == 15) __builtin_amdgcn_sched_barrier(0); }
;                 ss = xsum32(ss);
;                 const float rn = rsqrtf(ss * (1.0f / 128.0f) + 1e-5f) * p.one_minus_lam_init;
;                 const unsigned tok = (unsigned)(b * SEQ + iw + 32 * r + qle), zo = tok * (unsigned)ld + 4u * hhe, yo = tok * (unsigned)DM + 4u * hhe;
; #pragma unroll
;                 for (int t = 0; t < 4; ++t)
; #pragma unroll
;                     for (int i4 = 0; i4 < 4; ++i4) { const int dvc = 32 * t + 8 * i4, dv = dvc + 4 * hhe; const u32x2 z = *(const u32x2*)(zp + (zo + dvc)); const f32x4 sg = *(const f32x4*)(p.diff_subln_g + dv);
.LBB0_52:
	s_add_u32 s26, s87, s5
	s_addc_u32 s27, s86, 0
	s_lshl_b32 s2, s46, 13
	v_and_or_b32 v131, v130, 31, s2
	v_ashrrev_i32_e32 v130, 3, v130
	s_waitcnt lgkmcnt(0)
	s_barrier
	v_or_b32_e32 v204, s4, v131
	v_and_b32_e32 v130, -4, v130
	s_add_u32 s46, s80, s5
	v_cndmask_b32_e64 v131, 0, 1, s[48:49]
	s_addc_u32 s47, s81, 0
	v_cmp_ne_u32_e64 s[42:43], 1, v131
	s_andn2_b64 vcc, exec, s[48:49]
	v_ashrrev_i32_e32 v131, 31, v130
	s_cbranch_vccnz .LBB0_54
	v_div_scale_f32 v133, s[4:5], v132, v132, 1.0
	v_rcp_f32_e32 v134, v133
	ds_read2st64_b32 v[142:143], v1 offset1:1
	ds_read2st64_b32 v[146:147], v1 offset0:2 offset1:3
	ds_read2st64_b32 v[148:149], v1 offset0:4 offset1:5
	ds_read2st64_b32 v[150:151], v1 offset0:6 offset1:7
	ds_read2st64_b32 v[156:157], v1 offset0:8 offset1:9
	ds_read2st64_b32 v[158:159], v1 offset0:10 offset1:11
	ds_read2st64_b32 v[160:161], v1 offset0:12 offset1:13
	ds_read2st64_b32 v[208:209], v1 offset0:14 offset1:15
	v_fma_f32 v135, -v133, v134, 1.0
	v_fmac_f32_e32 v134, v135, v134
	v_div_scale_f32 v135, vcc, 1.0, v132, 1.0
	v_mul_f32_e32 v136, v135, v134
	v_fma_f32 v137, -v133, v136, v135
	v_fmac_f32_e32 v136, v137, v134
	v_fma_f32 v133, -v133, v136, v135
	v_div_fmas_f32 v133, v133, v134, v136
	v_div_fixup_f32 v144, v133, v132, 1.0
	ds_read2st64_b32 v[210:211], v1 offset0:16 offset1:17
	ds_read2st64_b32 v[214:215], v1 offset0:18 offset1:19
	ds_read2st64_b32 v[216:217], v1 offset0:20 offset1:21
	ds_read2st64_b32 v[218:219], v1 offset0:22 offset1:23
	ds_read2st64_b32 v[140:141], v1 offset0:24 offset1:25
	ds_read2st64_b32 v[136:137], v1 offset0:26 offset1:27
	ds_read2st64_b32 v[198:199], v1 offset0:28 offset1:29
	ds_read2st64_b32 v[202:203], v1 offset0:30 offset1:31
	ds_read2st64_b32 v[194:195], v1 offset0:32 offset1:33
	ds_read2st64_b32 v[196:197], v1 offset0:34 offset1:35
	ds_read2st64_b32 v[190:191], v1 offset0:36 offset1:37
	ds_read2st64_b32 v[192:193], v1 offset0:38 offset1:39
	ds_read2st64_b32 v[186:187], v1 offset0:40 offset1:41
	ds_read2st64_b32 v[188:189], v1 offset0:42 offset1:43
	ds_read2st64_b32 v[182:183], v1 offset0:44 offset1:45
	ds_read2st64_b32 v[184:185], v1 offset0:46 offset1:47
	ds_read2st64_b32 v[178:179], v1 offset0:48 offset1:49
	ds_read2st64_b32 v[180:181], v1 offset0:50 offset1:51
	ds_read2st64_b32 v[174:175], v1 offset0:52 offset1:53
	ds_read2st64_b32 v[176:177], v1 offset0:54 offset1:55
	ds_read2st64_b32 v[168:169], v1 offset0:56 offset1:57
	ds_read2st64_b32 v[172:173], v1 offset0:58 offset1:59
	ds_read2st64_b32 v[152:153], v1 offset0:60 offset1:61
	ds_read2st64_b32 v[166:167], v1 offset0:62 offset1:63
	v_lshl_add_u32 v138, v204, 12, v130
	s_movk_i32 s2, 0xf400
	v_mad_u64_u32 v[132:133], s[4:5], v204, s2, v[138:139]
	v_mov_b32_e32 v139, v0
	v_lshl_add_u64 v[134:135], v[138:139], 1, s[26:27]
	global_load_dwordx2 v[200:201], v[134:135], off
	v_readlane_b32 s92, v254, 42
	v_readlane_b32 s94, v254, 44
	v_readlane_b32 s95, v254, 45
	s_waitcnt lgkmcnt(14)
	v_pk_fma_f32 v[120:121], v[120:121], v[144:145], v[150:151] op_sel_hi:[1,0,1] neg_lo:[0,0,1] neg_hi:[0,0,1]
	v_pk_fma_f32 v[122:123], v[122:123], v[144:145], v[156:157] op_sel_hi:[1,0,1] neg_lo:[0,0,1] neg_hi:[0,0,1]
	v_lshl_add_u64 v[134:135], v[130:131], 2, s[94:95]
	v_pk_fma_f32 v[150:151], v[100:101], v[144:145], v[214:215] op_sel_hi:[1,0,1] neg_lo:[0,0,1] neg_hi:[0,0,1]
	v_pk_fma_f32 v[156:157], v[98:99], v[144:145], v[210:211] op_sel_hi:[1,0,1] neg_lo:[0,0,1] neg_hi:[0,0,1]
	global_load_dwordx4 v[98:101], v[134:135], off
	v_pk_fma_f32 v[154:155], v[114:115], v[144:145], v[142:143] op_sel_hi:[1,0,1] neg_lo:[0,0,1] neg_hi:[0,0,1]
	v_pk_fma_f32 v[170:171], v[118:119], v[144:145], v[148:149] op_sel_hi:[1,0,1] neg_lo:[0,0,1] neg_hi:[0,0,1]
	v_pk_fma_f32 v[148:149], v[102:103], v[144:145], v[216:217] op_sel_hi:[1,0,1] neg_lo:[0,0,1] neg_hi:[0,0,1]
	v_mul_f32_e32 v102, v155, v155
	v_pk_fma_f32 v[146:147], v[116:117], v[144:145], v[146:147] op_sel_hi:[1,0,1] neg_lo:[0,0,1] neg_hi:[0,0,1]
	v_pk_fma_f32 v[102:103], v[154:155], v[154:155], v[102:103] op_sel_hi:[1,1,0]
	v_pk_fma_f32 v[142:143], v[104:105], v[144:145], v[218:219] op_sel_hi:[1,0,1] neg_lo:[0,0,1] neg_hi:[0,0,1]
	v_mul_f32_e32 v104, v147, v147
	v_pk_fma_f32 v[102:103], v[146:147], v[146:147], v[102:103]
	v_pk_fma_f32 v[140:141], v[106:107], v[144:145], v[140:141] op_sel_hi:[1,0,1] neg_lo:[0,0,1] neg_hi:[0,0,1]
	v_pk_add_f32 v[102:103], v[102:103], v[104:105] op_sel_hi:[1,0]
	v_mul_f32_e32 v106, v171, v171
	v_pk_fma_f32 v[102:103], v[170:171], v[170:171], v[102:103]
	v_pk_fma_f32 v[136:137], v[108:109], v[144:145], v[136:137] op_sel_hi:[1,0,1] neg_lo:[0,0,1] neg_hi:[0,0,1]
	v_pk_add_f32 v[102:103], v[102:103], v[106:107] op_sel_hi:[1,0]
	v_mul_f32_e32 v108, v121, v121
	v_pk_fma_f32 v[102:103], v[120:121], v[120:121], v[102:103]
	v_pk_fma_f32 v[114:115], v[124:125], v[144:145], v[158:159] op_sel_hi:[1,0,1] neg_lo:[0,0,1] neg_hi:[0,0,1]
	v_pk_add_f32 v[102:103], v[102:103], v[108:109] op_sel_hi:[1,0]
	v_pk_fma_f32 v[124:125], v[112:113], v[144:145], v[202:203] op_sel_hi:[1,0,1] neg_lo:[0,0,1] neg_hi:[0,0,1]
	v_mul_f32_e32 v112, v123, v123
	v_pk_fma_f32 v[102:103], v[122:123], v[122:123], v[102:103]
	v_mul_f32_e32 v116, v115, v115
	v_pk_add_f32 v[102:103], v[102:103], v[112:113] op_sel_hi:[1,0]
	v_pk_fma_f32 v[160:161], v[126:127], v[144:145], v[160:161] op_sel_hi:[1,0,1] neg_lo:[0,0,1] neg_hi:[0,0,1]
	v_pk_fma_f32 v[102:103], v[114:115], v[114:115], v[102:103]
	v_mul_f32_e32 v118, v161, v161
	v_pk_add_f32 v[102:103], v[102:103], v[116:117] op_sel_hi:[1,0]
	v_pk_fma_f32 v[158:159], v[128:129], v[144:145], v[208:209] op_sel_hi:[1,0,1] neg_lo:[0,0,1] neg_hi:[0,0,1]
; __device__ __forceinline__ unsigned pk_bf16(float lo, float hi) { const f32x2 v = {lo, hi}; const bf16v2 b = __builtin_convertvector(v, bf16v2); return __builtin_bit_cast(unsigned, b); }
; __device__ __forceinline__ float bf_lo(unsigned u) { return __uint_as_float(u << 16); }
; __device__ __forceinline__ float bf_hi(unsigned u) { return __uint_as_float(u & 0xffff0000u); }
; __device__ __forceinline__ float silu_f(float v) { return v * __builtin_amdgcn_rcpf(1.0f + __builtin_amdgcn_exp2f(-LOG2E * v)); }
; __device__ __forceinline__ float xsum32(float v) { const auto r = __builtin_amdgcn_permlane32_swap(__float_as_uint(v), __float_as_uint(v), false, false); return __uint_as_float(r[0]) + __uint_as_float(r[1]); }
; __device__ __forceinline__ void diff_attn_phase(const Params& p, LAS unsigned char* lds) {
;     ...
;                 const float i0 = 1.0f / lt; float ss = 0.f;
; #pragma unroll
;                 for (int t = 0; t < 4; ++t)
; #pragma unroll
;                     for (int i = 0; i < 16; ++i) { const float a = O[r][t][i] * i0 - ex[(t * 16 + i) * 64]; O[r][t][i] = a; ss += a * a; if (i == 15) __builtin_amdgcn_sched_barrier(0); }
;                 ss = xsum32(ss);
;                 const float rn = rsqrtf(ss * (1.0f / 128.0f) + 1e-5f) * p.one_minus_lam_init;
;                 const unsigned tok = (unsigned)(b * SEQ + iw + 32 * r + qle), zo = tok * (unsigned)ld + 4u * hhe, yo = tok * (unsigned)DM + 4u * hhe;
; #pragma unroll
;                 for (int t = 0; t < 4; ++t)
; #pragma unroll
;                     for (int i4 = 0; i4 < 4; ++i4) { const int dvc = 32 * t + 8 * i4, dv = dvc + 4 * hhe; const u32x2 z = *(const u32x2*)(zp + (zo + dvc)); const f32x4 sg = *(const f32x4*)(p.diff_subln_g + dv);
;                         u32x2 wv; wv.x = pk_bf16(O[r][t][4 * i4] * rn * sg[0] * silu_f(bf_lo(z.x)), O[r][t][4 * i4 + 1] * rn * sg[1] * silu_f(bf_hi(z.x)));
	v_pk_fma_f32 v[102:103], v[160:161], v[160:161], v[102:103]
	v_mul_f32_e32 v128, v159, v159
	v_pk_add_f32 v[102:103], v[102:103], v[118:119] op_sel_hi:[1,0]
	v_pk_fma_f32 v[126:127], v[110:111], v[144:145], v[198:199] op_sel_hi:[1,0,1] neg_lo:[0,0,1] neg_hi:[0,0,1]
	v_pk_fma_f32 v[102:103], v[158:159], v[158:159], v[102:103]
	v_mul_f32_e32 v198, v157, v157
	v_pk_add_f32 v[102:103], v[102:103], v[128:129] op_sel_hi:[1,0]
	v_mul_f32_e32 v202, v151, v151
	v_pk_fma_f32 v[102:103], v[156:157], v[156:157], v[102:103]
	v_mul_f32_e32 v208, v149, v149
	v_pk_add_f32 v[102:103], v[102:103], v[198:199] op_sel_hi:[1,0]
	v_mul_f32_e32 v210, v143, v143
	v_pk_fma_f32 v[102:103], v[150:151], v[150:151], v[102:103]
	v_mul_f32_e32 v214, v141, v141
	v_pk_add_f32 v[102:103], v[102:103], v[202:203] op_sel_hi:[1,0]
	v_mul_f32_e32 v216, v137, v137
	v_pk_fma_f32 v[102:103], v[148:149], v[148:149], v[102:103]
	v_mul_f32_e32 v218, v127, v127
	v_pk_add_f32 v[102:103], v[102:103], v[208:209] op_sel_hi:[1,0]
	v_mul_f32_e32 v220, v125, v125
	v_pk_fma_f32 v[102:103], v[142:143], v[142:143], v[102:103]
	v_pk_fma_f32 v[118:119], v[82:83], v[144:145], v[194:195] op_sel_hi:[1,0,1] neg_lo:[0,0,1] neg_hi:[0,0,1]
	v_pk_add_f32 v[102:103], v[102:103], v[210:211] op_sel_hi:[1,0]
	v_pk_fma_f32 v[116:117], v[84:85], v[144:145], v[196:197] op_sel_hi:[1,0,1] neg_lo:[0,0,1] neg_hi:[0,0,1]
	v_pk_fma_f32 v[102:103], v[140:141], v[140:141], v[102:103]
	v_mul_f32_e32 v84, v119, v119
	v_pk_add_f32 v[102:103], v[102:103], v[214:215] op_sel_hi:[1,0]
	s_waitcnt lgkmcnt(3)
	v_pk_fma_f32 v[74:75], v[74:75], v[144:145], v[168:169] op_sel_hi:[1,0,1] neg_lo:[0,0,1] neg_hi:[0,0,1]
	v_pk_fma_f32 v[102:103], v[136:137], v[136:137], v[102:103]
	v_readlane_b32 s2, v254, 57
	v_pk_add_f32 v[102:103], v[102:103], v[216:217] op_sel_hi:[1,0]
	v_mov_b32_e32 v133, v0
	v_pk_fma_f32 v[102:103], v[126:127], v[126:127], v[102:103]
	v_lshl_add_u64 v[110:111], v[132:133], 1, s[46:47]
	v_pk_add_f32 v[102:103], v[102:103], v[218:219] op_sel_hi:[1,0]
	v_add_u32_e32 v168, 0x60, v138
	v_pk_fma_f32 v[102:103], v[124:125], v[124:125], v[102:103]
	v_mov_b32_e32 v169, v0
	v_pk_add_f32 v[102:103], v[102:103], v[220:221] op_sel_hi:[1,0]
	v_readlane_b32 s93, v254, 43
	v_pk_fma_f32 v[82:83], v[118:119], v[118:119], v[102:103]
	s_waitcnt vmcnt(1)
	v_lshlrev_b32_e32 v106, 16, v201
	v_and_b32_e32 v107, 0xffff0000, v201
	v_mul_f32_e32 v112, 0xbfb8aa3b, v106
	v_mul_f32_e32 v113, 0xbfb8aa3b, v107
	v_lshlrev_b32_e32 v104, 16, v200
	v_and_b32_e32 v105, 0xffff0000, v200
	v_exp_f32_e32 v112, v112
	v_exp_f32_e32 v113, v113
	v_mul_f32_e32 v108, 0xbfb8aa3b, v104
	v_mul_f32_e32 v109, 0xbfb8aa3b, v105
	v_exp_f32_e32 v108, v108
	v_exp_f32_e32 v109, v109
	v_add_f32_e32 v112, 1.0, v112
	v_add_f32_e32 v113, 1.0, v113
	v_rcp_f32_e32 v112, v112
	v_rcp_f32_e32 v113, v113
	v_add_f32_e32 v108, 1.0, v108
	v_add_f32_e32 v109, 1.0, v109
	v_rcp_f32_e32 v108, v108
	v_rcp_f32_e32 v109, v109
	v_pk_add_f32 v[82:83], v[82:83], v[84:85] op_sel_hi:[1,0]
	v_mul_f32_e32 v84, v117, v117
	v_pk_fma_f32 v[82:83], v[116:117], v[116:117], v[82:83]
	v_pk_mul_f32 v[198:199], v[112:113], v[106:107]
	v_pk_add_f32 v[82:83], v[82:83], v[84:85] op_sel_hi:[1,0]
	v_pk_fma_f32 v[112:113], v[86:87], v[144:145], v[190:191] op_sel_hi:[1,0,1] neg_lo:[0,0,1] neg_hi:[0,0,1]
	v_pk_mul_f32 v[128:129], v[108:109], v[104:105]
	v_pk_fma_f32 v[82:83], v[112:113], v[112:113], v[82:83]
	v_mul_f32_e32 v84, v113, v113
	v_pk_fma_f32 v[108:109], v[88:89], v[144:145], v[192:193] op_sel_hi:[1,0,1] neg_lo:[0,0,1] neg_hi:[0,0,1]
	v_pk_add_f32 v[82:83], v[82:83], v[84:85] op_sel_hi:[1,0]
	v_mul_f32_e32 v84, v109, v109
	v_pk_fma_f32 v[82:83], v[108:109], v[108:109], v[82:83]
	v_pk_fma_f32 v[106:107], v[90:91], v[144:145], v[186:187] op_sel_hi:[1,0,1] neg_lo:[0,0,1] neg_hi:[0,0,1]
	v_pk_add_f32 v[82:83], v[82:83], v[84:85] op_sel_hi:[1,0]
	v_mul_f32_e32 v84, v107, v107
	v_pk_fma_f32 v[82:83], v[106:107], v[106:107], v[82:83]
	v_pk_fma_f32 v[104:105], v[92:93], v[144:145], v[188:189] op_sel_hi:[1,0,1] neg_lo:[0,0,1] neg_hi:[0,0,1]
	v_pk_add_f32 v[82:83], v[82:83], v[84:85] op_sel_hi:[1,0]
	v_mul_f32_e32 v84, v105, v105
	v_pk_fma_f32 v[82:83], v[104:105], v[104:105], v[82:83]
	v_pk_fma_f32 v[102:103], v[94:95], v[144:145], v[182:183] op_sel_hi:[1,0,1] neg_lo:[0,0,1] neg_hi:[0,0,1]
	v_pk_add_f32 v[82:83], v[82:83], v[84:85] op_sel_hi:[1,0]
	v_mul_f32_e32 v84, v103, v103
	v_pk_fma_f32 v[82:83], v[102:103], v[102:103], v[82:83]
	v_pk_fma_f32 v[92:93], v[96:97], v[144:145], v[184:185] op_sel_hi:[1,0,1] neg_lo:[0,0,1] neg_hi:[0,0,1]
	v_pk_add_f32 v[82:83], v[82:83], v[84:85] op_sel_hi:[1,0]
	v_mul_f32_e32 v84, v93, v93
	v_pk_fma_f32 v[82:83], v[92:93], v[92:93], v[82:83]
	v_pk_fma_f32 v[90:91], v[66:67], v[144:145], v[178:179] op_sel_hi:[1,0,1] neg_lo:[0,0,1] neg_hi:[0,0,1]
	v_pk_add_f32 v[82:83], v[82:83], v[84:85] op_sel_hi:[1,0]
	v_pk_fma_f32 v[86:87], v[68:69], v[144:145], v[180:181] op_sel_hi:[1,0,1] neg_lo:[0,0,1] neg_hi:[0,0,1]
	v_pk_fma_f32 v[66:67], v[90:91], v[90:91], v[82:83]
	v_mul_f32_e32 v68, v91, v91
	v_pk_add_f32 v[66:67], v[66:67], v[68:69] op_sel_hi:[1,0]
	v_mul_f32_e32 v68, v87, v87
	v_pk_fma_f32 v[66:67], v[86:87], v[86:87], v[66:67]
	v_pk_fma_f32 v[84:85], v[70:71], v[144:145], v[174:175] op_sel_hi:[1,0,1] neg_lo:[0,0,1] neg_hi:[0,0,1]
	v_pk_add_f32 v[66:67], v[66:67], v[68:69] op_sel_hi:[1,0]
	v_mul_f32_e32 v68, v85, v85
	v_pk_fma_f32 v[66:67], v[84:85], v[84:85], v[66:67]
	v_pk_fma_f32 v[82:83], v[72:73], v[144:145], v[176:177] op_sel_hi:[1,0,1] neg_lo:[0,0,1] neg_hi:[0,0,1]
	v_pk_add_f32 v[66:67], v[66:67], v[68:69] op_sel_hi:[1,0]
	v_mul_f32_e32 v68, v83, v83
	v_pk_fma_f32 v[66:67], v[82:83], v[82:83], v[66:67]
	s_waitcnt lgkmcnt(2)
; __device__ __forceinline__ unsigned pk_bf16(float lo, float hi) { const f32x2 v = {lo, hi}; const bf16v2 b = __builtin_convertvector(v, bf16v2); return __builtin_bit_cast(unsigned, b); }
; __device__ __forceinline__ float bf_lo(unsigned u) { return __uint_as_float(u << 16); }
; __device__ __forceinline__ float bf_hi(unsigned u) { return __uint_as_float(u & 0xffff0000u); }
; __device__ __forceinline__ float silu_f(float v) { return v * __builtin_amdgcn_rcpf(1.0f + __builtin_amdgcn_exp2f(-LOG2E * v)); }
; __device__ __forceinline__ float xsum32(float v) { const auto r = __builtin_amdgcn_permlane32_swap(__float_as_uint(v), __float_as_uint(v), false, false); return __uint_as_float(r[0]) + __uint_as_float(r[1]); }
; __device__ __forceinline__ void diff_attn_phase(const Params& p, LAS unsigned char* lds) {
;     ...
;                 ss = xsum32(ss);
;                 const float rn = rsqrtf(ss * (1.0f / 128.0f) + 1e-5f) * p.one_minus_lam_init;
;                 const unsigned tok = (unsigned)(b * SEQ + iw + 32 * r + qle), zo = tok * (unsigned)ld + 4u * hhe, yo = tok * (unsigned)DM + 4u * hhe;
; #pragma unroll
;                 for (int t = 0; t < 4; ++t)
; #pragma unroll
;                     for (int i4 = 0; i4 < 4; ++i4) { const int dvc = 32 * t + 8 * i4, dv = dvc + 4 * hhe; const u32x2 z = *(const u32x2*)(zp + (zo + dvc)); const f32x4 sg = *(const f32x4*)(p.diff_subln_g + dv);
;                         u32x2 wv; wv.x = pk_bf16(O[r][t][4 * i4] * rn * sg[0] * silu_f(bf_lo(z.x)), O[r][t][4 * i4 + 1] * rn * sg[1] * silu_f(bf_hi(z.x)));
;                         wv.y = pk_bf16(O[r][t][4 * i4 + 2] * rn * sg[2] * silu_f(bf_lo(z.y)), O[r][t][4 * i4 + 3] * rn * sg[3] * silu_f(bf_hi(z.y)));
;                         *(u32x2*)(Y + h * 128 + (yo + dvc)) = wv; if (i4 == 3) __builtin_amdgcn_sched_barrier(0); }
	v_pk_fma_f32 v[72:73], v[76:77], v[144:145], v[172:173] op_sel_hi:[1,0,1] neg_lo:[0,0,1] neg_hi:[0,0,1]
	v_pk_add_f32 v[66:67], v[66:67], v[68:69] op_sel_hi:[1,0]
	v_mul_f32_e32 v68, v75, v75
	v_pk_fma_f32 v[66:67], v[74:75], v[74:75], v[66:67]
	s_waitcnt lgkmcnt(1)
	v_pk_fma_f32 v[70:71], v[78:79], v[144:145], v[152:153] op_sel_hi:[1,0,1] neg_lo:[0,0,1] neg_hi:[0,0,1]
	v_pk_add_f32 v[66:67], v[66:67], v[68:69] op_sel_hi:[1,0]
	v_mul_f32_e32 v68, v73, v73
	v_pk_fma_f32 v[66:67], v[72:73], v[72:73], v[66:67]
	v_mul_f32_e32 v76, v71, v71
	v_pk_add_f32 v[68:69], v[66:67], v[68:69] op_sel_hi:[1,0]
	s_waitcnt lgkmcnt(0)
	v_pk_fma_f32 v[66:67], v[80:81], v[144:145], v[166:167] op_sel_hi:[1,0,1] neg_lo:[0,0,1] neg_hi:[0,0,1]
	v_pk_fma_f32 v[68:69], v[70:71], v[70:71], v[68:69]
	v_add_u32_e32 v88, 8, v132
	v_pk_add_f32 v[68:69], v[68:69], v[76:77] op_sel_hi:[1,0]
	v_mul_f32_e32 v76, v67, v67
	v_pk_fma_f32 v[68:69], v[66:67], v[66:67], v[68:69]
	v_mov_b32_e32 v89, v0
	v_pk_add_f32 v[68:69], v[68:69], v[76:77] op_sel_hi:[1,0]
	v_lshl_add_u64 v[88:89], v[88:89], 1, s[46:47]
	v_mov_b32_e32 v69, v68
	s_nop 1
	v_permlane32_swap_b32_e32 v68, v69
	v_add_f32_e32 v68, v68, v69
	v_mov_b32_e32 v69, 0x3727c5ac
	v_fmamk_f32 v68, v68, 0x3c000000, v69
	v_mul_f32_e32 v69, 0x4b800000, v68
	v_cmp_gt_f32_e32 vcc, s82, v68
	v_add_u32_e32 v94, 16, v138
	v_mov_b32_e32 v95, v0
	v_cndmask_b32_e32 v68, v68, v69, vcc
	v_rsq_f32_e32 v78, v68
	v_add_u32_e32 v68, 8, v138
	v_mov_b32_e32 v69, v0
	v_lshl_add_u64 v[76:77], v[68:69], 1, s[26:27]
	v_mul_f32_e32 v68, 0x45800000, v78
	v_cndmask_b32_e32 v68, v78, v68, vcc
	v_mul_f32_e32 v68, s2, v68
	v_pk_mul_f32 v[78:79], v[154:155], v[68:69] op_sel_hi:[1,0]
	v_pk_mul_f32 v[80:81], v[146:147], v[68:69] op_sel_hi:[1,0]
	s_waitcnt vmcnt(0)
	v_pk_mul_f32 v[78:79], v[98:99], v[78:79]
	v_pk_mul_f32 v[80:81], v[100:101], v[80:81]
	v_pk_mul_f32 v[78:79], v[128:129], v[78:79]
	v_pk_mul_f32 v[80:81], v[198:199], v[80:81]
	v_cvt_pk_bf16_f32 v78, v78, v79
	v_cvt_pk_bf16_f32 v79, v80, v81
	global_store_dwordx2 v[110:111], v[78:79], off
	global_load_dwordx2 v[138:139], v[76:77], off
	global_load_dwordx4 v[144:147], v[134:135], off offset:32
	global_load_dwordx2 v[166:167], v[76:77], off offset:16
	global_load_dwordx4 v[152:155], v[134:135], off offset:64
	global_load_dwordx2 v[168:169], v[76:77], off offset:32
	global_load_dwordx4 v[172:175], v[134:135], off offset:96
	global_load_dwordx2 v[180:181], v[76:77], off offset:48
	global_load_dwordx4 v[176:179], v[134:135], off offset:128
	global_load_dwordx2 v[182:183], v[76:77], off offset:64
	global_load_dwordx4 v[184:187], v[134:135], off offset:160
	global_load_dwordx2 v[192:193], v[76:77], off offset:80
	global_load_dwordx4 v[188:191], v[134:135], off offset:192
	global_load_dwordx2 v[194:195], v[76:77], off offset:96
	global_load_dwordx4 v[196:199], v[134:135], off offset:224
	global_load_dwordx2 v[214:215], v[76:77], off offset:112
	global_load_dwordx4 v[200:203], v[134:135], off offset:256
	global_load_dwordx2 v[222:223], v[76:77], off offset:128
	global_load_dwordx4 v[216:219], v[134:135], off offset:288
	global_load_dwordx2 v[228:229], v[76:77], off offset:144
	global_load_dwordx4 v[224:227], v[134:135], off offset:320
	s_waitcnt vmcnt(18)
	v_lshlrev_b32_e32 v80, 16, v138
	v_and_b32_e32 v81, 0xffff0000, v138
	v_lshlrev_b32_e32 v88, 16, v139
	v_and_b32_e32 v89, 0xffff0000, v139
	v_mul_f32_e32 v94, 0xbfb8aa3b, v80
	v_mul_f32_e32 v95, 0xbfb8aa3b, v81
	v_mul_f32_e32 v96, 0xbfb8aa3b, v88
	v_mul_f32_e32 v97, 0xbfb8aa3b, v89
	v_exp_f32_e32 v94, v94
	v_exp_f32_e32 v95, v95
	v_exp_f32_e32 v96, v96
	v_exp_f32_e32 v97, v97
	v_add_f32_e32 v94, 1.0, v94
	v_add_f32_e32 v95, 1.0, v95
	v_add_f32_e32 v96, 1.0, v96
	v_add_f32_e32 v97, 1.0, v97
	v_rcp_f32_e32 v94, v94
	v_rcp_f32_e32 v95, v95
	v_rcp_f32_e32 v96, v96
	v_rcp_f32_e32 v97, v97
	v_pk_mul_f32 v[98:99], v[170:171], v[68:69] op_sel_hi:[1,0]
	v_pk_mul_f32 v[100:101], v[120:121], v[68:69] op_sel_hi:[1,0]
	v_pk_mul_f32 v[98:99], v[144:145], v[98:99]
	v_pk_mul_f32 v[100:101], v[146:147], v[100:101]
	v_pk_mul_f32 v[80:81], v[94:95], v[80:81]
	v_pk_mul_f32 v[88:89], v[96:97], v[88:89]
	v_pk_mul_f32 v[98:99], v[98:99], v[80:81]
	v_pk_mul_f32 v[100:101], v[100:101], v[88:89]
	v_cvt_pk_bf16_f32 v128, v98, v99
	v_cvt_pk_bf16_f32 v129, v100, v101
	global_store_dwordx2 v[110:111], v[128:129], off offset:16
	global_load_dwordx2 v[138:139], v[76:77], off offset:160
	global_load_dwordx4 v[144:147], v[134:135], off offset:352
	s_waitcnt vmcnt(19)
	v_lshlrev_b32_e32 v80, 16, v166
	v_and_b32_e32 v81, 0xffff0000, v166
	v_lshlrev_b32_e32 v88, 16, v167
	v_and_b32_e32 v89, 0xffff0000, v167
	v_mul_f32_e32 v94, 0xbfb8aa3b, v80
	v_mul_f32_e32 v95, 0xbfb8aa3b, v81
	v_mul_f32_e32 v96, 0xbfb8aa3b, v88
	v_mul_f32_e32 v97, 0xbfb8aa3b, v89
	v_exp_f32_e32 v94, v94
	v_exp_f32_e32 v95, v95
	v_exp_f32_e32 v96, v96
	v_exp_f32_e32 v97, v97
	v_add_f32_e32 v94, 1.0, v94
	v_add_f32_e32 v95, 1.0, v95
	v_add_f32_e32 v96, 1.0, v96
	v_add_f32_e32 v97, 1.0, v97
	v_rcp_f32_e32 v94, v94
	v_rcp_f32_e32 v95, v95
	v_rcp_f32_e32 v96, v96
	v_rcp_f32_e32 v97, v97
	v_pk_mul_f32 v[98:99], v[122:123], v[68:69] op_sel_hi:[1,0]
	v_pk_mul_f32 v[100:101], v[114:115], v[68:69] op_sel_hi:[1,0]
	v_pk_mul_f32 v[98:99], v[152:153], v[98:99]
	v_pk_mul_f32 v[100:101], v[154:155], v[100:101]
	v_pk_mul_f32 v[80:81], v[94:95], v[80:81]
	v_pk_mul_f32 v[88:89], v[96:97], v[88:89]
	v_pk_mul_f32 v[98:99], v[98:99], v[80:81]
	v_pk_mul_f32 v[100:101], v[100:101], v[88:89]
	v_cvt_pk_bf16_f32 v132, v98, v99
	v_cvt_pk_bf16_f32 v133, v100, v101
	global_store_dwordx2 v[110:111], v[132:133], off offset:32
	global_load_dwordx2 v[166:167], v[76:77], off offset:176
	global_load_dwordx4 v[152:155], v[134:135], off offset:384
	s_waitcnt vmcnt(20)
; __device__ __forceinline__ unsigned pk_bf16(float lo, float hi) { const f32x2 v = {lo, hi}; const bf16v2 b = __builtin_convertvector(v, bf16v2); return __builtin_bit_cast(unsigned, b); }
; __device__ __forceinline__ float bf_lo(unsigned u) { return __uint_as_float(u << 16); }
; __device__ __forceinline__ float bf_hi(unsigned u) { return __uint_as_float(u & 0xffff0000u); }
; __device__ __forceinline__ float silu_f(float v) { return v * __builtin_amdgcn_rcpf(1.0f + __builtin_amdgcn_exp2f(-LOG2E * v)); }
; __device__ __forceinline__ void diff_attn_phase(const Params& p, LAS unsigned char* lds) {
;     ...
; #pragma unroll
;                 for (int t = 0; t < 4; ++t)
; #pragma unroll
;                     for (int i4 = 0; i4 < 4; ++i4) { const int dvc = 32 * t + 8 * i4, dv = dvc + 4 * hhe; const u32x2 z = *(const u32x2*)(zp + (zo + dvc)); const f32x4 sg = *(const f32x4*)(p.diff_subln_g + dv);
;                         u32x2 wv; wv.x = pk_bf16(O[r][t][4 * i4] * rn * sg[0] * silu_f(bf_lo(z.x)), O[r][t][4 * i4 + 1] * rn * sg[1] * silu_f(bf_hi(z.x)));
;                         wv.y = pk_bf16(O[r][t][4 * i4 + 2] * rn * sg[2] * silu_f(bf_lo(z.y)), O[r][t][4 * i4 + 3] * rn * sg[3] * silu_f(bf_hi(z.y)));
;                         *(u32x2*)(Y + h * 128 + (yo + dvc)) = wv; if (i4 == 3) __builtin_amdgcn_sched_barrier(0); }
	v_lshlrev_b32_e32 v80, 16, v168
	v_and_b32_e32 v81, 0xffff0000, v168
	v_lshlrev_b32_e32 v88, 16, v169
	v_and_b32_e32 v89, 0xffff0000, v169
	v_mul_f32_e32 v94, 0xbfb8aa3b, v80
	v_mul_f32_e32 v95, 0xbfb8aa3b, v81
	v_mul_f32_e32 v96, 0xbfb8aa3b, v88
	v_mul_f32_e32 v97, 0xbfb8aa3b, v89
	v_exp_f32_e32 v94, v94
	v_exp_f32_e32 v95, v95
	v_exp_f32_e32 v96, v96
	v_exp_f32_e32 v97, v97
	v_add_f32_e32 v94, 1.0, v94
	v_add_f32_e32 v95, 1.0, v95
	v_add_f32_e32 v96, 1.0, v96
	v_add_f32_e32 v97, 1.0, v97
	v_rcp_f32_e32 v94, v94
	v_rcp_f32_e32 v95, v95
	v_rcp_f32_e32 v96, v96
	v_rcp_f32_e32 v97, v97
	v_pk_mul_f32 v[98:99], v[160:161], v[68:69] op_sel_hi:[1,0]
	v_pk_mul_f32 v[100:101], v[158:159], v[68:69] op_sel_hi:[1,0]
	v_pk_mul_f32 v[98:99], v[172:173], v[98:99]
	v_pk_mul_f32 v[100:101], v[174:175], v[100:101]
	v_pk_mul_f32 v[80:81], v[94:95], v[80:81]
	v_pk_mul_f32 v[88:89], v[96:97], v[88:89]
	v_pk_mul_f32 v[98:99], v[98:99], v[80:81]
	v_pk_mul_f32 v[100:101], v[100:101], v[88:89]
	v_cvt_pk_bf16_f32 v128, v98, v99
	v_cvt_pk_bf16_f32 v129, v100, v101
	global_store_dwordx2 v[110:111], v[128:129], off offset:48
	global_load_dwordx2 v[168:169], v[76:77], off offset:192
	global_load_dwordx4 v[172:175], v[134:135], off offset:416
	s_waitcnt vmcnt(21)
	v_lshlrev_b32_e32 v80, 16, v180
	v_and_b32_e32 v81, 0xffff0000, v180
	v_lshlrev_b32_e32 v88, 16, v181
	v_and_b32_e32 v89, 0xffff0000, v181
	v_mul_f32_e32 v94, 0xbfb8aa3b, v80
	v_mul_f32_e32 v95, 0xbfb8aa3b, v81
	v_mul_f32_e32 v96, 0xbfb8aa3b, v88
	v_mul_f32_e32 v97, 0xbfb8aa3b, v89
	v_exp_f32_e32 v94, v94
	v_exp_f32_e32 v95, v95
	v_exp_f32_e32 v96, v96
	v_exp_f32_e32 v97, v97
	v_add_f32_e32 v94, 1.0, v94
	v_add_f32_e32 v95, 1.0, v95
	v_add_f32_e32 v96, 1.0, v96
	v_add_f32_e32 v97, 1.0, v97
	v_rcp_f32_e32 v94, v94
	v_rcp_f32_e32 v95, v95
	v_rcp_f32_e32 v96, v96
	v_rcp_f32_e32 v97, v97
	v_pk_mul_f32 v[98:99], v[156:157], v[68:69] op_sel_hi:[1,0]
	v_pk_mul_f32 v[100:101], v[150:151], v[68:69] op_sel_hi:[1,0]
	v_pk_mul_f32 v[98:99], v[176:177], v[98:99]
	v_pk_mul_f32 v[100:101], v[178:179], v[100:101]
	v_pk_mul_f32 v[80:81], v[94:95], v[80:81]
	v_pk_mul_f32 v[88:89], v[96:97], v[88:89]
	v_pk_mul_f32 v[98:99], v[98:99], v[80:81]
	v_pk_mul_f32 v[100:101], v[100:101], v[88:89]
	v_cvt_pk_bf16_f32 v132, v98, v99
	v_cvt_pk_bf16_f32 v133, v100, v101
	global_store_dwordx2 v[110:111], v[132:133], off offset:64
	global_load_dwordx2 v[180:181], v[76:77], off offset:208
	global_load_dwordx4 v[176:179], v[134:135], off offset:448
	s_waitcnt vmcnt(22)
	v_lshlrev_b32_e32 v80, 16, v182
	v_and_b32_e32 v81, 0xffff0000, v182
	v_lshlrev_b32_e32 v88, 16, v183
	v_and_b32_e32 v89, 0xffff0000, v183
	v_mul_f32_e32 v94, 0xbfb8aa3b, v80
	v_mul_f32_e32 v95, 0xbfb8aa3b, v81
	v_mul_f32_e32 v96, 0xbfb8aa3b, v88
	v_mul_f32_e32 v97, 0xbfb8aa3b, v89
	v_exp_f32_e32 v94, v94
	v_exp_f32_e32 v95, v95
	v_exp_f32_e32 v96, v96
	v_exp_f32_e32 v97, v97
	v_add_f32_e32 v94, 1.0, v94
	v_add_f32_e32 v95, 1.0, v95
	v_add_f32_e32 v96, 1.0, v96
	v_add_f32_e32 v97, 1.0, v97
	v_rcp_f32_e32 v94, v94
	v_rcp_f32_e32 v95, v95
	v_rcp_f32_e32 v96, v96
	v_rcp_f32_e32 v97, v97
	v_pk_mul_f32 v[98:99], v[148:149], v[68:69] op_sel_hi:[1,0]
	v_pk_mul_f32 v[100:101], v[142:143], v[68:69] op_sel_hi:[1,0]
	v_pk_mul_f32 v[98:99], v[184:185], v[98:99]
	v_pk_mul_f32 v[100:101], v[186:187], v[100:101]
	v_pk_mul_f32 v[80:81], v[94:95], v[80:81]
	v_pk_mul_f32 v[88:89], v[96:97], v[88:89]
	v_pk_mul_f32 v[98:99], v[98:99], v[80:81]
	v_pk_mul_f32 v[100:101], v[100:101], v[88:89]
	v_cvt_pk_bf16_f32 v128, v98, v99
	v_cvt_pk_bf16_f32 v129, v100, v101
	global_store_dwordx2 v[110:111], v[128:129], off offset:80
	global_load_dwordx2 v[182:183], v[76:77], off offset:224
	global_load_dwordx4 v[184:187], v[134:135], off offset:480
	s_waitcnt vmcnt(23)
	v_lshlrev_b32_e32 v80, 16, v192
	v_and_b32_e32 v81, 0xffff0000, v192
	v_lshlrev_b32_e32 v88, 16, v193
	v_and_b32_e32 v89, 0xffff0000, v193
	v_mul_f32_e32 v94, 0xbfb8aa3b, v80
	v_mul_f32_e32 v95, 0xbfb8aa3b, v81
	v_mul_f32_e32 v96, 0xbfb8aa3b, v88
	v_mul_f32_e32 v97, 0xbfb8aa3b, v89
	v_exp_f32_e32 v94, v94
	v_exp_f32_e32 v95, v95
	v_exp_f32_e32 v96, v96
	v_exp_f32_e32 v97, v97
	v_add_f32_e32 v94, 1.0, v94
	v_add_f32_e32 v95, 1.0, v95
	v_add_f32_e32 v96, 1.0, v96
	v_add_f32_e32 v97, 1.0, v97
	v_rcp_f32_e32 v94, v94
	v_rcp_f32_e32 v95, v95
	v_rcp_f32_e32 v96, v96
	v_rcp_f32_e32 v97, v97
	v_pk_mul_f32 v[98:99], v[140:141], v[68:69] op_sel_hi:[1,0]
	v_pk_mul_f32 v[100:101], v[136:137], v[68:69] op_sel_hi:[1,0]
	v_pk_mul_f32 v[98:99], v[188:189], v[98:99]
	v_pk_mul_f32 v[100:101], v[190:191], v[100:101]
	v_pk_mul_f32 v[80:81], v[94:95], v[80:81]
	v_pk_mul_f32 v[88:89], v[96:97], v[88:89]
	v_pk_mul_f32 v[98:99], v[98:99], v[80:81]
	v_pk_mul_f32 v[100:101], v[100:101], v[88:89]
	v_cvt_pk_bf16_f32 v132, v98, v99
	v_cvt_pk_bf16_f32 v133, v100, v101
	global_store_dwordx2 v[110:111], v[132:133], off offset:96
	s_waitcnt vmcnt(22)
	v_lshlrev_b32_e32 v80, 16, v194
	v_and_b32_e32 v81, 0xffff0000, v194
	v_lshlrev_b32_e32 v88, 16, v195
	v_and_b32_e32 v89, 0xffff0000, v195
	v_mul_f32_e32 v94, 0xbfb8aa3b, v80
	v_mul_f32_e32 v95, 0xbfb8aa3b, v81
	v_mul_f32_e32 v96, 0xbfb8aa3b, v88
	v_mul_f32_e32 v97, 0xbfb8aa3b, v89
	v_exp_f32_e32 v94, v94
	v_exp_f32_e32 v95, v95
	v_exp_f32_e32 v96, v96
	v_exp_f32_e32 v97, v97
	v_add_f32_e32 v94, 1.0, v94
	v_add_f32_e32 v95, 1.0, v95
	v_add_f32_e32 v96, 1.0, v96
	v_add_f32_e32 v97, 1.0, v97
	v_rcp_f32_e32 v94, v94
	v_rcp_f32_e32 v95, v95
	v_rcp_f32_e32 v96, v96
	v_rcp_f32_e32 v97, v97
	v_pk_mul_f32 v[98:99], v[126:127], v[68:69] op_sel_hi:[1,0]
	v_pk_mul_f32 v[100:101], v[124:125], v[68:69] op_sel_hi:[1,0]
	v_pk_mul_f32 v[98:99], v[196:197], v[98:99]
	v_pk_mul_f32 v[100:101], v[198:199], v[100:101]
	v_pk_mul_f32 v[80:81], v[94:95], v[80:81]
	v_pk_mul_f32 v[88:89], v[96:97], v[88:89]
	v_pk_mul_f32 v[98:99], v[98:99], v[80:81]
	v_pk_mul_f32 v[100:101], v[100:101], v[88:89]
	v_cvt_pk_bf16_f32 v128, v98, v99
	v_cvt_pk_bf16_f32 v129, v100, v101
	global_store_dwordx2 v[110:111], v[128:129], off offset:112
	s_waitcnt vmcnt(21)
; __device__ __forceinline__ unsigned pk_bf16(float lo, float hi) { const f32x2 v = {lo, hi}; const bf16v2 b = __builtin_convertvector(v, bf16v2); return __builtin_bit_cast(unsigned, b); }
; __device__ __forceinline__ float bf_lo(unsigned u) { return __uint_as_float(u << 16); }
; __device__ __forceinline__ float bf_hi(unsigned u) { return __uint_as_float(u & 0xffff0000u); }
; __device__ __forceinline__ float silu_f(float v) { return v * __builtin_amdgcn_rcpf(1.0f + __builtin_amdgcn_exp2f(-LOG2E * v)); }
; __device__ __forceinline__ void diff_attn_phase(const Params& p, LAS unsigned char* lds) {
;     ...
; #pragma unroll
;                 for (int t = 0; t < 4; ++t)
; #pragma unroll
;                     for (int i4 = 0; i4 < 4; ++i4) { const int dvc = 32 * t + 8 * i4, dv = dvc + 4 * hhe; const u32x2 z = *(const u32x2*)(zp + (zo + dvc)); const f32x4 sg = *(const f32x4*)(p.diff_subln_g + dv);
;                         u32x2 wv; wv.x = pk_bf16(O[r][t][4 * i4] * rn * sg[0] * silu_f(bf_lo(z.x)), O[r][t][4 * i4 + 1] * rn * sg[1] * silu_f(bf_hi(z.x)));
;                         wv.y = pk_bf16(O[r][t][4 * i4 + 2] * rn * sg[2] * silu_f(bf_lo(z.y)), O[r][t][4 * i4 + 3] * rn * sg[3] * silu_f(bf_hi(z.y)));
;                         *(u32x2*)(Y + h * 128 + (yo + dvc)) = wv; if (i4 == 3) __builtin_amdgcn_sched_barrier(0); }
	v_lshlrev_b32_e32 v80, 16, v214
	v_and_b32_e32 v81, 0xffff0000, v214
	v_lshlrev_b32_e32 v88, 16, v215
	v_and_b32_e32 v89, 0xffff0000, v215
	v_mul_f32_e32 v94, 0xbfb8aa3b, v80
	v_mul_f32_e32 v95, 0xbfb8aa3b, v81
	v_mul_f32_e32 v96, 0xbfb8aa3b, v88
	v_mul_f32_e32 v97, 0xbfb8aa3b, v89
	v_exp_f32_e32 v94, v94
	v_exp_f32_e32 v95, v95
	v_exp_f32_e32 v96, v96
	v_exp_f32_e32 v97, v97
	v_add_f32_e32 v94, 1.0, v94
	v_add_f32_e32 v95, 1.0, v95
	v_add_f32_e32 v96, 1.0, v96
	v_add_f32_e32 v97, 1.0, v97
	v_rcp_f32_e32 v94, v94
	v_rcp_f32_e32 v95, v95
	v_rcp_f32_e32 v96, v96
	v_rcp_f32_e32 v97, v97
	v_pk_mul_f32 v[98:99], v[118:119], v[68:69] op_sel_hi:[1,0]
	v_pk_mul_f32 v[100:101], v[116:117], v[68:69] op_sel_hi:[1,0]
	v_pk_mul_f32 v[98:99], v[200:201], v[98:99]
	v_pk_mul_f32 v[100:101], v[202:203], v[100:101]
	v_pk_mul_f32 v[80:81], v[94:95], v[80:81]
	v_pk_mul_f32 v[88:89], v[96:97], v[88:89]
	v_pk_mul_f32 v[98:99], v[98:99], v[80:81]
	v_pk_mul_f32 v[100:101], v[100:101], v[88:89]
	v_cvt_pk_bf16_f32 v132, v98, v99
	v_cvt_pk_bf16_f32 v133, v100, v101
	global_store_dwordx2 v[110:111], v[132:133], off offset:128
	s_waitcnt vmcnt(20)
	v_lshlrev_b32_e32 v80, 16, v222
	v_and_b32_e32 v81, 0xffff0000, v222
	v_lshlrev_b32_e32 v88, 16, v223
	v_and_b32_e32 v89, 0xffff0000, v223
	v_mul_f32_e32 v94, 0xbfb8aa3b, v80
	v_mul_f32_e32 v95, 0xbfb8aa3b, v81
	v_mul_f32_e32 v96, 0xbfb8aa3b, v88
	v_mul_f32_e32 v97, 0xbfb8aa3b, v89
	v_exp_f32_e32 v94, v94
	v_exp_f32_e32 v95, v95
	v_exp_f32_e32 v96, v96
	v_exp_f32_e32 v97, v97
	v_add_f32_e32 v94, 1.0, v94
	v_add_f32_e32 v95, 1.0, v95
	v_add_f32_e32 v96, 1.0, v96
	v_add_f32_e32 v97, 1.0, v97
	v_rcp_f32_e32 v94, v94
	v_rcp_f32_e32 v95, v95
	v_rcp_f32_e32 v96, v96
	v_rcp_f32_e32 v97, v97
	v_pk_mul_f32 v[98:99], v[112:113], v[68:69] op_sel_hi:[1,0]
	v_pk_mul_f32 v[100:101], v[108:109], v[68:69] op_sel_hi:[1,0]
	v_pk_mul_f32 v[98:99], v[216:217], v[98:99]
	v_pk_mul_f32 v[100:101], v[218:219], v[100:101]
	v_pk_mul_f32 v[80:81], v[94:95], v[80:81]
	v_pk_mul_f32 v[88:89], v[96:97], v[88:89]
	v_pk_mul_f32 v[98:99], v[98:99], v[80:81]
	v_pk_mul_f32 v[100:101], v[100:101], v[88:89]
	v_cvt_pk_bf16_f32 v128, v98, v99
	v_cvt_pk_bf16_f32 v129, v100, v101
	global_store_dwordx2 v[110:111], v[128:129], off offset:144
	s_waitcnt vmcnt(19)
	v_lshlrev_b32_e32 v80, 16, v228
	v_and_b32_e32 v81, 0xffff0000, v228
	v_lshlrev_b32_e32 v88, 16, v229
	v_and_b32_e32 v89, 0xffff0000, v229
	v_mul_f32_e32 v94, 0xbfb8aa3b, v80
	v_mul_f32_e32 v95, 0xbfb8aa3b, v81
	v_mul_f32_e32 v96, 0xbfb8aa3b, v88
	v_mul_f32_e32 v97, 0xbfb8aa3b, v89
	v_exp_f32_e32 v94, v94
	v_exp_f32_e32 v95, v95
	v_exp_f32_e32 v96, v96
	v_exp_f32_e32 v97, v97
	v_add_f32_e32 v94, 1.0, v94
	v_add_f32_e32 v95, 1.0, v95
	v_add_f32_e32 v96, 1.0, v96
	v_add_f32_e32 v97, 1.0, v97
	v_rcp_f32_e32 v94, v94
	v_rcp_f32_e32 v95, v95
	v_rcp_f32_e32 v96, v96
	v_rcp_f32_e32 v97, v97
	v_pk_mul_f32 v[98:99], v[106:107], v[68:69] op_sel_hi:[1,0]
	v_pk_mul_f32 v[100:101], v[104:105], v[68:69] op_sel_hi:[1,0]
	v_pk_mul_f32 v[98:99], v[224:225], v[98:99]
	v_pk_mul_f32 v[100:101], v[226:227], v[100:101]
	v_pk_mul_f32 v[80:81], v[94:95], v[80:81]
	v_pk_mul_f32 v[88:89], v[96:97], v[88:89]
	v_pk_mul_f32 v[98:99], v[98:99], v[80:81]
	v_pk_mul_f32 v[100:101], v[100:101], v[88:89]
	v_cvt_pk_bf16_f32 v132, v98, v99
	v_cvt_pk_bf16_f32 v133, v100, v101
	global_store_dwordx2 v[110:111], v[132:133], off offset:160
	s_waitcnt vmcnt(17)
	v_lshlrev_b32_e32 v80, 16, v138
	v_and_b32_e32 v81, 0xffff0000, v138
	v_lshlrev_b32_e32 v88, 16, v139
	v_and_b32_e32 v89, 0xffff0000, v139
	v_mul_f32_e32 v94, 0xbfb8aa3b, v80
	v_mul_f32_e32 v95, 0xbfb8aa3b, v81
	v_mul_f32_e32 v96, 0xbfb8aa3b, v88
	v_mul_f32_e32 v97, 0xbfb8aa3b, v89
	v_exp_f32_e32 v94, v94
	v_exp_f32_e32 v95, v95
	v_exp_f32_e32 v96, v96
	v_exp_f32_e32 v97, v97
	v_add_f32_e32 v94, 1.0, v94
	v_add_f32_e32 v95, 1.0, v95
	v_add_f32_e32 v96, 1.0, v96
	v_add_f32_e32 v97, 1.0, v97
	v_rcp_f32_e32 v94, v94
	v_rcp_f32_e32 v95, v95
	v_rcp_f32_e32 v96, v96
	v_rcp_f32_e32 v97, v97
	v_pk_mul_f32 v[98:99], v[102:103], v[68:69] op_sel_hi:[1,0]
	v_pk_mul_f32 v[100:101], v[92:93], v[68:69] op_sel_hi:[1,0]
	v_pk_mul_f32 v[98:99], v[144:145], v[98:99]
	v_pk_mul_f32 v[100:101], v[146:147], v[100:101]
	v_pk_mul_f32 v[80:81], v[94:95], v[80:81]
	v_pk_mul_f32 v[88:89], v[96:97], v[88:89]
	v_pk_mul_f32 v[98:99], v[98:99], v[80:81]
	v_pk_mul_f32 v[100:101], v[100:101], v[88:89]
	v_cvt_pk_bf16_f32 v128, v98, v99
	v_cvt_pk_bf16_f32 v129, v100, v101
	global_store_dwordx2 v[110:111], v[128:129], off offset:176
	s_waitcnt vmcnt(15)
; __device__ __forceinline__ unsigned pk_bf16(float lo, float hi) { const f32x2 v = {lo, hi}; const bf16v2 b = __builtin_convertvector(v, bf16v2); return __builtin_bit_cast(unsigned, b); }
; __device__ __forceinline__ float bf_lo(unsigned u) { return __uint_as_float(u << 16); }
; __device__ __forceinline__ float bf_hi(unsigned u) { return __uint_as_float(u & 0xffff0000u); }
; __device__ __forceinline__ float silu_f(float v) { return v * __builtin_amdgcn_rcpf(1.0f + __builtin_amdgcn_exp2f(-LOG2E * v)); }
; __device__ __forceinline__ void diff_attn_phase(const Params& p, LAS unsigned char* lds) {
;     ...
;                     for (int i4 = 0; i4 < 4; ++i4) { const int dvc = 32 * t + 8 * i4, dv = dvc + 4 * hhe; const u32x2 z = *(const u32x2*)(zp + (zo + dvc)); const f32x4 sg = *(const f32x4*)(p.diff_subln_g + dv);
;                         u32x2 wv; wv.x = pk_bf16(O[r][t][4 * i4] * rn * sg[0] * silu_f(bf_lo(z.x)), O[r][t][4 * i4 + 1] * rn * sg[1] * silu_f(bf_hi(z.x)));
;                         wv.y = pk_bf16(O[r][t][4 * i4 + 2] * rn * sg[2] * silu_f(bf_lo(z.y)), O[r][t][4 * i4 + 3] * rn * sg[3] * silu_f(bf_hi(z.y)));
;                         *(u32x2*)(Y + h * 128 + (yo + dvc)) = wv; if (i4 == 3) __builtin_amdgcn_sched_barrier(0); }
	v_lshlrev_b32_e32 v80, 16, v166
	v_and_b32_e32 v81, 0xffff0000, v166
	v_lshlrev_b32_e32 v88, 16, v167
	v_and_b32_e32 v89, 0xffff0000, v167
	v_mul_f32_e32 v94, 0xbfb8aa3b, v80
	v_mul_f32_e32 v95, 0xbfb8aa3b, v81
	v_mul_f32_e32 v96, 0xbfb8aa3b, v88
	v_mul_f32_e32 v97, 0xbfb8aa3b, v89
	v_exp_f32_e32 v94, v94
	v_exp_f32_e32 v95, v95
	v_exp_f32_e32 v96, v96
	v_exp_f32_e32 v97, v97
	v_add_f32_e32 v94, 1.0, v94
	v_add_f32_e32 v95, 1.0, v95
	v_add_f32_e32 v96, 1.0, v96
	v_add_f32_e32 v97, 1.0, v97
	v_rcp_f32_e32 v94, v94
	v_rcp_f32_e32 v95, v95
	v_rcp_f32_e32 v96, v96
	v_rcp_f32_e32 v97, v97
	v_pk_mul_f32 v[98:99], v[90:91], v[68:69] op_sel_hi:[1,0]
	v_pk_mul_f32 v[100:101], v[86:87], v[68:69] op_sel_hi:[1,0]
	v_pk_mul_f32 v[98:99], v[152:153], v[98:99]
	v_pk_mul_f32 v[100:101], v[154:155], v[100:101]
	v_pk_mul_f32 v[80:81], v[94:95], v[80:81]
	v_pk_mul_f32 v[88:89], v[96:97], v[88:89]
	v_pk_mul_f32 v[98:99], v[98:99], v[80:81]
	v_pk_mul_f32 v[100:101], v[100:101], v[88:89]
	v_cvt_pk_bf16_f32 v132, v98, v99
	v_cvt_pk_bf16_f32 v133, v100, v101
	global_store_dwordx2 v[110:111], v[132:133], off offset:192
	s_waitcnt vmcnt(13)
	v_lshlrev_b32_e32 v80, 16, v168
	v_and_b32_e32 v81, 0xffff0000, v168
	v_lshlrev_b32_e32 v88, 16, v169
	v_and_b32_e32 v89, 0xffff0000, v169
	v_mul_f32_e32 v94, 0xbfb8aa3b, v80
	v_mul_f32_e32 v95, 0xbfb8aa3b, v81
	v_mul_f32_e32 v96, 0xbfb8aa3b, v88
	v_mul_f32_e32 v97, 0xbfb8aa3b, v89
	v_exp_f32_e32 v94, v94
	v_exp_f32_e32 v95, v95
	v_exp_f32_e32 v96, v96
	v_exp_f32_e32 v97, v97
	v_add_f32_e32 v94, 1.0, v94
	v_add_f32_e32 v95, 1.0, v95
	v_add_f32_e32 v96, 1.0, v96
	v_add_f32_e32 v97, 1.0, v97
	v_rcp_f32_e32 v94, v94
	v_rcp_f32_e32 v95, v95
	v_rcp_f32_e32 v96, v96
	v_rcp_f32_e32 v97, v97
	v_pk_mul_f32 v[98:99], v[84:85], v[68:69] op_sel_hi:[1,0]
	v_pk_mul_f32 v[100:101], v[82:83], v[68:69] op_sel_hi:[1,0]
	v_pk_mul_f32 v[98:99], v[172:173], v[98:99]
	v_pk_mul_f32 v[100:101], v[174:175], v[100:101]
	v_pk_mul_f32 v[80:81], v[94:95], v[80:81]
	v_pk_mul_f32 v[88:89], v[96:97], v[88:89]
	v_pk_mul_f32 v[98:99], v[98:99], v[80:81]
	v_pk_mul_f32 v[100:101], v[100:101], v[88:89]
	v_cvt_pk_bf16_f32 v128, v98, v99
	v_cvt_pk_bf16_f32 v129, v100, v101
	global_store_dwordx2 v[110:111], v[128:129], off offset:208
	s_waitcnt vmcnt(11)
	v_lshlrev_b32_e32 v80, 16, v180
	v_and_b32_e32 v81, 0xffff0000, v180
	v_lshlrev_b32_e32 v88, 16, v181
	v_and_b32_e32 v89, 0xffff0000, v181
	v_mul_f32_e32 v94, 0xbfb8aa3b, v80
	v_mul_f32_e32 v95, 0xbfb8aa3b, v81
	v_mul_f32_e32 v96, 0xbfb8aa3b, v88
	v_mul_f32_e32 v97, 0xbfb8aa3b, v89
	v_exp_f32_e32 v94, v94
	v_exp_f32_e32 v95, v95
	v_exp_f32_e32 v96, v96
	v_exp_f32_e32 v97, v97
	v_add_f32_e32 v94, 1.0, v94
	v_add_f32_e32 v95, 1.0, v95
	v_add_f32_e32 v96, 1.0, v96
	v_add_f32_e32 v97, 1.0, v97
	v_rcp_f32_e32 v94, v94
	v_rcp_f32_e32 v95, v95
	v_rcp_f32_e32 v96, v96
	v_rcp_f32_e32 v97, v97
	v_pk_mul_f32 v[98:99], v[74:75], v[68:69] op_sel_hi:[1,0]
	v_pk_mul_f32 v[100:101], v[72:73], v[68:69] op_sel_hi:[1,0]
	v_pk_mul_f32 v[98:99], v[176:177], v[98:99]
	v_pk_mul_f32 v[100:101], v[178:179], v[100:101]
	v_pk_mul_f32 v[80:81], v[94:95], v[80:81]
	v_pk_mul_f32 v[88:89], v[96:97], v[88:89]
	v_pk_mul_f32 v[98:99], v[98:99], v[80:81]
	v_pk_mul_f32 v[100:101], v[100:101], v[88:89]
	v_cvt_pk_bf16_f32 v132, v98, v99
	v_cvt_pk_bf16_f32 v133, v100, v101
	global_store_dwordx2 v[110:111], v[132:133], off offset:224
	s_waitcnt vmcnt(9)
	v_lshlrev_b32_e32 v80, 16, v182
	v_and_b32_e32 v81, 0xffff0000, v182
	v_lshlrev_b32_e32 v88, 16, v183
	v_and_b32_e32 v89, 0xffff0000, v183
	v_mul_f32_e32 v94, 0xbfb8aa3b, v80
	v_mul_f32_e32 v95, 0xbfb8aa3b, v81
	v_mul_f32_e32 v96, 0xbfb8aa3b, v88
	v_mul_f32_e32 v97, 0xbfb8aa3b, v89
	v_exp_f32_e32 v94, v94
	v_exp_f32_e32 v95, v95
	v_exp_f32_e32 v96, v96
	v_exp_f32_e32 v97, v97
	v_add_f32_e32 v94, 1.0, v94
	v_add_f32_e32 v95, 1.0, v95
	v_add_f32_e32 v96, 1.0, v96
	v_add_f32_e32 v97, 1.0, v97
	v_rcp_f32_e32 v94, v94
	v_rcp_f32_e32 v95, v95
	v_rcp_f32_e32 v96, v96
	v_rcp_f32_e32 v97, v97
	v_pk_mul_f32 v[98:99], v[70:71], v[68:69] op_sel_hi:[1,0]
	v_pk_mul_f32 v[100:101], v[66:67], v[68:69] op_sel_hi:[1,0]
	v_pk_mul_f32 v[98:99], v[184:185], v[98:99]
	v_pk_mul_f32 v[100:101], v[186:187], v[100:101]
	v_pk_mul_f32 v[80:81], v[94:95], v[80:81]
	v_pk_mul_f32 v[88:89], v[96:97], v[88:89]
	v_pk_mul_f32 v[98:99], v[98:99], v[80:81]
	v_pk_mul_f32 v[100:101], v[100:101], v[88:89]
	v_cvt_pk_bf16_f32 v128, v98, v99
	v_cvt_pk_bf16_f32 v129, v100, v101
	global_store_dwordx2 v[110:111], v[128:129], off offset:240

; __device__ __forceinline__ float xsum32(float v) { const auto r = __builtin_amdgcn_permlane32_swap(__float_as_uint(v), __float_as_uint(v), false, false); return __uint_as_float(r[0]) + __uint_as_float(r[1]); }
; __device__ __forceinline__ void diff_attn_phase(const Params& p, LAS unsigned char* lds) {
;     ...
;             asm volatile("s_waitcnt lgkmcnt(0)" ::: "memory"); __builtin_amdgcn_s_barrier(); asm volatile("" ::: "memory");
;             if (comp == 0) {
;                 const float i0 = 1.0f / lt; float ss = 0.f;
; #pragma unroll
;                 for (int t = 0; t < 4; ++t)
; #pragma unroll
;                     for (int i = 0; i < 16; ++i) { const float a = O[r][t][i] * i0 - ex[(t * 16 + i) * 64]; O[r][t][i] = a; ss += a * a; if (i == 15) __builtin_amdgcn_sched_barrier(0); }
;                 ss = xsum32(ss);
;                 const float rn = rsqrtf(ss * (1.0f / 128.0f) + 1e-5f) * p.one_minus_lam_init;
;                 const unsigned tok = (unsigned)(b * SEQ + iw + 32 * r + qle), zo = tok * (unsigned)ld + 4u * hhe, yo = tok * (unsigned)DM + 4u * hhe;
; #pragma unroll
;                 for (int t = 0; t < 4; ++t)
; #pragma unroll
;                     for (int i4 = 0; i4 < 4; ++i4) { const int dvc = 32 * t + 8 * i4, dv = dvc + 4 * hhe; const u32x2 z = *(const u32x2*)(zp + (zo + dvc)); const f32x4 sg = *(const f32x4*)(p.diff_subln_g + dv);
.LBB0_56:
	s_waitcnt lgkmcnt(0)
	s_barrier
	s_and_b64 vcc, exec, s[42:43]
	s_cbranch_vccnz .LBB0_37
	v_div_scale_f32 v67, s[4:5], v66, v66, 1.0
	v_rcp_f32_e32 v68, v67
	ds_read2st64_b32 v[76:77], v1 offset1:1
	ds_read2st64_b32 v[80:81], v1 offset0:2 offset1:3
	ds_read2st64_b32 v[82:83], v1 offset0:4 offset1:5
	ds_read2st64_b32 v[84:85], v1 offset0:6 offset1:7
	ds_read2st64_b32 v[90:91], v1 offset0:8 offset1:9
	ds_read2st64_b32 v[92:93], v1 offset0:10 offset1:11
	ds_read2st64_b32 v[94:95], v1 offset0:12 offset1:13
	ds_read2st64_b32 v[136:137], v1 offset0:14 offset1:15
	v_fma_f32 v69, -v67, v68, 1.0
	v_fmac_f32_e32 v68, v69, v68
	v_div_scale_f32 v69, vcc, 1.0, v66, 1.0
	v_mul_f32_e32 v70, v69, v68
	v_fma_f32 v71, -v67, v70, v69
	v_fmac_f32_e32 v70, v71, v68
	v_fma_f32 v67, -v67, v70, v69
	v_div_fmas_f32 v67, v67, v68, v70
	v_div_fixup_f32 v78, v67, v66, 1.0
	ds_read2st64_b32 v[138:139], v1 offset0:16 offset1:17
	ds_read2st64_b32 v[140:141], v1 offset0:18 offset1:19
	ds_read2st64_b32 v[142:143], v1 offset0:20 offset1:21
	ds_read2st64_b32 v[144:145], v1 offset0:22 offset1:23
	ds_read2st64_b32 v[74:75], v1 offset0:24 offset1:25
	ds_read2st64_b32 v[70:71], v1 offset0:26 offset1:27
	ds_read2st64_b32 v[128:129], v1 offset0:28 offset1:29
	ds_read2st64_b32 v[132:133], v1 offset0:30 offset1:31
	ds_read2st64_b32 v[124:125], v1 offset0:32 offset1:33
	ds_read2st64_b32 v[126:127], v1 offset0:34 offset1:35
	ds_read2st64_b32 v[120:121], v1 offset0:36 offset1:37
	ds_read2st64_b32 v[122:123], v1 offset0:38 offset1:39
	ds_read2st64_b32 v[116:117], v1 offset0:40 offset1:41
	ds_read2st64_b32 v[118:119], v1 offset0:42 offset1:43
	ds_read2st64_b32 v[112:113], v1 offset0:44 offset1:45
	ds_read2st64_b32 v[114:115], v1 offset0:46 offset1:47
	ds_read2st64_b32 v[108:109], v1 offset0:48 offset1:49
	ds_read2st64_b32 v[110:111], v1 offset0:50 offset1:51
	ds_read2st64_b32 v[104:105], v1 offset0:52 offset1:53
	ds_read2st64_b32 v[106:107], v1 offset0:54 offset1:55
	ds_read2st64_b32 v[98:99], v1 offset0:56 offset1:57
	ds_read2st64_b32 v[102:103], v1 offset0:58 offset1:59
	ds_read2st64_b32 v[86:87], v1 offset0:60 offset1:61
	ds_read2st64_b32 v[96:97], v1 offset0:62 offset1:63
	v_or_b32_e32 v1, 32, v204
	v_lshl_add_u32 v72, v1, 12, v130
	s_movk_i32 s2, 0xf400
	v_mad_u64_u32 v[66:67], s[4:5], v1, s2, v[72:73]
	v_mov_b32_e32 v73, v0
	v_lshl_add_u64 v[68:69], v[72:73], 1, s[26:27]
	global_load_dwordx2 v[134:135], v[68:69], off
	v_readlane_b32 s92, v254, 42
	v_readlane_b32 s94, v254, 44
	v_readlane_b32 s95, v254, 45
	s_waitcnt lgkmcnt(14)
	v_pk_fma_f32 v[56:57], v[56:57], v[78:79], v[84:85] op_sel_hi:[1,0,1] neg_lo:[0,0,1] neg_hi:[0,0,1]
	v_pk_fma_f32 v[58:59], v[58:59], v[78:79], v[90:91] op_sel_hi:[1,0,1] neg_lo:[0,0,1] neg_hi:[0,0,1]
	v_lshl_add_u64 v[68:69], v[130:131], 2, s[94:95]
	v_pk_fma_f32 v[84:85], v[36:37], v[78:79], v[140:141] op_sel_hi:[1,0,1] neg_lo:[0,0,1] neg_hi:[0,0,1]
	v_pk_fma_f32 v[90:91], v[34:35], v[78:79], v[138:139] op_sel_hi:[1,0,1] neg_lo:[0,0,1] neg_hi:[0,0,1]
	global_load_dwordx4 v[34:37], v[68:69], off
	v_pk_fma_f32 v[88:89], v[50:51], v[78:79], v[76:77] op_sel_hi:[1,0,1] neg_lo:[0,0,1] neg_hi:[0,0,1]
	v_pk_fma_f32 v[100:101], v[54:55], v[78:79], v[82:83] op_sel_hi:[1,0,1] neg_lo:[0,0,1] neg_hi:[0,0,1]
	v_pk_fma_f32 v[82:83], v[38:39], v[78:79], v[142:143] op_sel_hi:[1,0,1] neg_lo:[0,0,1] neg_hi:[0,0,1]
	v_mul_f32_e32 v38, v89, v89
	v_pk_fma_f32 v[80:81], v[52:53], v[78:79], v[80:81] op_sel_hi:[1,0,1] neg_lo:[0,0,1] neg_hi:[0,0,1]
	v_pk_fma_f32 v[38:39], v[88:89], v[88:89], v[38:39] op_sel_hi:[1,1,0]
	v_pk_fma_f32 v[76:77], v[40:41], v[78:79], v[144:145] op_sel_hi:[1,0,1] neg_lo:[0,0,1] neg_hi:[0,0,1]
	v_mul_f32_e32 v40, v81, v81
	v_pk_fma_f32 v[38:39], v[80:81], v[80:81], v[38:39]
	v_pk_fma_f32 v[74:75], v[42:43], v[78:79], v[74:75] op_sel_hi:[1,0,1] neg_lo:[0,0,1] neg_hi:[0,0,1]
	v_pk_add_f32 v[38:39], v[38:39], v[40:41] op_sel_hi:[1,0]
	v_mul_f32_e32 v42, v101, v101
	v_pk_fma_f32 v[38:39], v[100:101], v[100:101], v[38:39]
	v_pk_fma_f32 v[70:71], v[44:45], v[78:79], v[70:71] op_sel_hi:[1,0,1] neg_lo:[0,0,1] neg_hi:[0,0,1]
	v_pk_add_f32 v[38:39], v[38:39], v[42:43] op_sel_hi:[1,0]
	v_mul_f32_e32 v44, v57, v57
	v_pk_fma_f32 v[38:39], v[56:57], v[56:57], v[38:39]
	v_pk_fma_f32 v[50:51], v[60:61], v[78:79], v[92:93] op_sel_hi:[1,0,1] neg_lo:[0,0,1] neg_hi:[0,0,1]
	v_pk_add_f32 v[38:39], v[38:39], v[44:45] op_sel_hi:[1,0]
	v_pk_fma_f32 v[60:61], v[48:49], v[78:79], v[132:133] op_sel_hi:[1,0,1] neg_lo:[0,0,1] neg_hi:[0,0,1]
	v_mul_f32_e32 v48, v59, v59
	v_pk_fma_f32 v[38:39], v[58:59], v[58:59], v[38:39]
	v_mul_f32_e32 v52, v51, v51
	v_pk_add_f32 v[38:39], v[38:39], v[48:49] op_sel_hi:[1,0]
	v_pk_fma_f32 v[94:95], v[62:63], v[78:79], v[94:95] op_sel_hi:[1,0,1] neg_lo:[0,0,1] neg_hi:[0,0,1]
	v_pk_fma_f32 v[38:39], v[50:51], v[50:51], v[38:39]
	v_mul_f32_e32 v54, v95, v95
	v_pk_add_f32 v[38:39], v[38:39], v[52:53] op_sel_hi:[1,0]
	v_pk_fma_f32 v[92:93], v[64:65], v[78:79], v[136:137] op_sel_hi:[1,0,1] neg_lo:[0,0,1] neg_hi:[0,0,1]
	v_pk_fma_f32 v[38:39], v[94:95], v[94:95], v[38:39]
	v_mul_f32_e32 v64, v93, v93
	v_pk_add_f32 v[38:39], v[38:39], v[54:55] op_sel_hi:[1,0]
	v_pk_fma_f32 v[62:63], v[46:47], v[78:79], v[128:129] op_sel_hi:[1,0,1] neg_lo:[0,0,1] neg_hi:[0,0,1]
	v_pk_fma_f32 v[38:39], v[92:93], v[92:93], v[38:39]
	v_mul_f32_e32 v128, v91, v91
	v_pk_add_f32 v[38:39], v[38:39], v[64:65] op_sel_hi:[1,0]
	v_mul_f32_e32 v130, v85, v85
	v_pk_fma_f32 v[38:39], v[90:91], v[90:91], v[38:39]
	v_mul_f32_e32 v132, v83, v83
	v_pk_add_f32 v[38:39], v[38:39], v[128:129] op_sel_hi:[1,0]
	v_mul_f32_e32 v136, v77, v77
	v_pk_fma_f32 v[38:39], v[84:85], v[84:85], v[38:39]
	v_mul_f32_e32 v138, v75, v75
	v_pk_add_f32 v[38:39], v[38:39], v[130:131] op_sel_hi:[1,0]
	v_mul_f32_e32 v140, v71, v71
	v_pk_fma_f32 v[38:39], v[82:83], v[82:83], v[38:39]
	v_mul_f32_e32 v142, v63, v63
	v_pk_add_f32 v[38:39], v[38:39], v[132:133] op_sel_hi:[1,0]
	v_mul_f32_e32 v144, v61, v61
	v_pk_fma_f32 v[38:39], v[76:77], v[76:77], v[38:39]
	v_pk_fma_f32 v[54:55], v[18:19], v[78:79], v[124:125] op_sel_hi:[1,0,1] neg_lo:[0,0,1] neg_hi:[0,0,1]
	v_pk_add_f32 v[38:39], v[38:39], v[136:137] op_sel_hi:[1,0]
	s_waitcnt lgkmcnt(3)
; __device__ __forceinline__ unsigned pk_bf16(float lo, float hi) { const f32x2 v = {lo, hi}; const bf16v2 b = __builtin_convertvector(v, bf16v2); return __builtin_bit_cast(unsigned, b); }
; __device__ __forceinline__ float bf_lo(unsigned u) { return __uint_as_float(u << 16); }
; __device__ __forceinline__ float bf_hi(unsigned u) { return __uint_as_float(u & 0xffff0000u); }
; __device__ __forceinline__ float silu_f(float v) { return v * __builtin_amdgcn_rcpf(1.0f + __builtin_amdgcn_exp2f(-LOG2E * v)); }
; __device__ __forceinline__ float xsum32(float v) { const auto r = __builtin_amdgcn_permlane32_swap(__float_as_uint(v), __float_as_uint(v), false, false); return __uint_as_float(r[0]) + __uint_as_float(r[1]); }
; __device__ __forceinline__ void diff_attn_phase(const Params& p, LAS unsigned char* lds) {
;     ...
;                     for (int i = 0; i < 16; ++i) { const float a = O[r][t][i] * i0 - ex[(t * 16 + i) * 64]; O[r][t][i] = a; ss += a * a; if (i == 15) __builtin_amdgcn_sched_barrier(0); }
;                 ss = xsum32(ss);
;                 const float rn = rsqrtf(ss * (1.0f / 128.0f) + 1e-5f) * p.one_minus_lam_init;
;                 const unsigned tok = (unsigned)(b * SEQ + iw + 32 * r + qle), zo = tok * (unsigned)ld + 4u * hhe, yo = tok * (unsigned)DM + 4u * hhe;
; #pragma unroll
;                 for (int t = 0; t < 4; ++t)
; #pragma unroll
;                     for (int i4 = 0; i4 < 4; ++i4) { const int dvc = 32 * t + 8 * i4, dv = dvc + 4 * hhe; const u32x2 z = *(const u32x2*)(zp + (zo + dvc)); const f32x4 sg = *(const f32x4*)(p.diff_subln_g + dv);
;                         u32x2 wv; wv.x = pk_bf16(O[r][t][4 * i4] * rn * sg[0] * silu_f(bf_lo(z.x)), O[r][t][4 * i4 + 1] * rn * sg[1] * silu_f(bf_hi(z.x)));
;                         wv.y = pk_bf16(O[r][t][4 * i4 + 2] * rn * sg[2] * silu_f(bf_lo(z.y)), O[r][t][4 * i4 + 3] * rn * sg[3] * silu_f(bf_hi(z.y)));
;                         *(u32x2*)(Y + h * 128 + (yo + dvc)) = wv; if (i4 == 3) __builtin_amdgcn_sched_barrier(0); }
	v_pk_fma_f32 v[10:11], v[10:11], v[78:79], v[98:99] op_sel_hi:[1,0,1] neg_lo:[0,0,1] neg_hi:[0,0,1]
	v_pk_fma_f32 v[38:39], v[74:75], v[74:75], v[38:39]
	v_readlane_b32 s2, v254, 57
	v_pk_add_f32 v[38:39], v[38:39], v[138:139] op_sel_hi:[1,0]
	v_mov_b32_e32 v67, v0
	v_pk_fma_f32 v[38:39], v[70:71], v[70:71], v[38:39]
	v_lshl_add_u64 v[46:47], v[66:67], 1, s[46:47]
	v_pk_add_f32 v[38:39], v[38:39], v[140:141] op_sel_hi:[1,0]
	v_add_u32_e32 v98, 0x60, v72
	v_pk_fma_f32 v[38:39], v[62:63], v[62:63], v[38:39]
	v_mov_b32_e32 v99, v0
	v_pk_add_f32 v[38:39], v[38:39], v[142:143] op_sel_hi:[1,0]
	v_readlane_b32 s93, v254, 43
	v_pk_fma_f32 v[38:39], v[60:61], v[60:61], v[38:39]
	s_waitcnt vmcnt(1)
	v_and_b32_e32 v41, 0xffff0000, v134
	v_lshlrev_b32_e32 v42, 16, v135
	v_and_b32_e32 v43, 0xffff0000, v135
	v_mul_f32_e32 v44, 0xbfb8aa3b, v41
	v_mul_f32_e32 v45, 0xbfb8aa3b, v42
	v_mul_f32_e32 v48, 0xbfb8aa3b, v43
	v_lshlrev_b32_e32 v40, 16, v134
	v_exp_f32_e32 v44, v44
	v_exp_f32_e32 v45, v45
	v_exp_f32_e32 v48, v48
	v_mul_f32_e32 v1, 0xbfb8aa3b, v40
	v_exp_f32_e32 v1, v1
	v_add_f32_e32 v49, 1.0, v44
	v_add_f32_e32 v52, 1.0, v45
	v_add_f32_e32 v53, 1.0, v48
	v_rcp_f32_e32 v45, v49
	v_rcp_f32_e32 v48, v52
	v_rcp_f32_e32 v49, v53
	v_pk_add_f32 v[38:39], v[38:39], v[144:145] op_sel_hi:[1,0]
	v_add_f32_e32 v1, 1.0, v1
	v_pk_fma_f32 v[52:53], v[20:21], v[78:79], v[126:127] op_sel_hi:[1,0,1] neg_lo:[0,0,1] neg_hi:[0,0,1]
	v_pk_fma_f32 v[18:19], v[54:55], v[54:55], v[38:39]
	v_mul_f32_e32 v20, v55, v55
	v_rcp_f32_e32 v44, v1
	v_pk_add_f32 v[18:19], v[18:19], v[20:21] op_sel_hi:[1,0]
	v_mul_f32_e32 v20, v53, v53
	v_pk_fma_f32 v[18:19], v[52:53], v[52:53], v[18:19]
	v_pk_mul_f32 v[128:129], v[48:49], v[42:43]
	v_pk_add_f32 v[18:19], v[18:19], v[20:21] op_sel_hi:[1,0]
	v_pk_fma_f32 v[48:49], v[22:23], v[78:79], v[120:121] op_sel_hi:[1,0,1] neg_lo:[0,0,1] neg_hi:[0,0,1]
	v_pk_mul_f32 v[64:65], v[44:45], v[40:41]
	v_pk_fma_f32 v[18:19], v[48:49], v[48:49], v[18:19]
	v_mul_f32_e32 v20, v49, v49
	v_pk_fma_f32 v[44:45], v[24:25], v[78:79], v[122:123] op_sel_hi:[1,0,1] neg_lo:[0,0,1] neg_hi:[0,0,1]
	v_pk_add_f32 v[18:19], v[18:19], v[20:21] op_sel_hi:[1,0]
	v_mul_f32_e32 v20, v45, v45
	v_pk_fma_f32 v[18:19], v[44:45], v[44:45], v[18:19]
	v_pk_fma_f32 v[42:43], v[26:27], v[78:79], v[116:117] op_sel_hi:[1,0,1] neg_lo:[0,0,1] neg_hi:[0,0,1]
	v_pk_add_f32 v[18:19], v[18:19], v[20:21] op_sel_hi:[1,0]
	v_mul_f32_e32 v20, v43, v43
	v_pk_fma_f32 v[18:19], v[42:43], v[42:43], v[18:19]
	v_pk_fma_f32 v[40:41], v[28:29], v[78:79], v[118:119] op_sel_hi:[1,0,1] neg_lo:[0,0,1] neg_hi:[0,0,1]
	v_pk_add_f32 v[18:19], v[18:19], v[20:21] op_sel_hi:[1,0]
	v_mul_f32_e32 v20, v41, v41
	v_pk_fma_f32 v[18:19], v[40:41], v[40:41], v[18:19]
	v_pk_fma_f32 v[38:39], v[30:31], v[78:79], v[112:113] op_sel_hi:[1,0,1] neg_lo:[0,0,1] neg_hi:[0,0,1]
	v_pk_add_f32 v[18:19], v[18:19], v[20:21] op_sel_hi:[1,0]
	v_mul_f32_e32 v20, v39, v39
	v_pk_fma_f32 v[18:19], v[38:39], v[38:39], v[18:19]
	v_pk_fma_f32 v[28:29], v[32:33], v[78:79], v[114:115] op_sel_hi:[1,0,1] neg_lo:[0,0,1] neg_hi:[0,0,1]
	v_pk_add_f32 v[18:19], v[18:19], v[20:21] op_sel_hi:[1,0]
	v_mul_f32_e32 v20, v29, v29
	v_pk_fma_f32 v[18:19], v[28:29], v[28:29], v[18:19]
	v_pk_fma_f32 v[26:27], v[2:3], v[78:79], v[108:109] op_sel_hi:[1,0,1] neg_lo:[0,0,1] neg_hi:[0,0,1]
	v_pk_add_f32 v[18:19], v[18:19], v[20:21] op_sel_hi:[1,0]
	v_pk_fma_f32 v[22:23], v[4:5], v[78:79], v[110:111] op_sel_hi:[1,0,1] neg_lo:[0,0,1] neg_hi:[0,0,1]
	v_pk_fma_f32 v[2:3], v[26:27], v[26:27], v[18:19]
	v_mul_f32_e32 v4, v27, v27
	v_pk_add_f32 v[2:3], v[2:3], v[4:5] op_sel_hi:[1,0]
	v_mul_f32_e32 v4, v23, v23
	v_pk_fma_f32 v[2:3], v[22:23], v[22:23], v[2:3]
	v_pk_fma_f32 v[20:21], v[6:7], v[78:79], v[104:105] op_sel_hi:[1,0,1] neg_lo:[0,0,1] neg_hi:[0,0,1]
	v_pk_add_f32 v[2:3], v[2:3], v[4:5] op_sel_hi:[1,0]
	v_mul_f32_e32 v4, v21, v21
	v_pk_fma_f32 v[2:3], v[20:21], v[20:21], v[2:3]
	v_pk_fma_f32 v[18:19], v[8:9], v[78:79], v[106:107] op_sel_hi:[1,0,1] neg_lo:[0,0,1] neg_hi:[0,0,1]
	v_pk_add_f32 v[2:3], v[2:3], v[4:5] op_sel_hi:[1,0]
	v_mul_f32_e32 v4, v19, v19
	v_pk_fma_f32 v[2:3], v[18:19], v[18:19], v[2:3]
	s_waitcnt lgkmcnt(2)
	v_pk_fma_f32 v[8:9], v[12:13], v[78:79], v[102:103] op_sel_hi:[1,0,1] neg_lo:[0,0,1] neg_hi:[0,0,1]
	v_pk_add_f32 v[2:3], v[2:3], v[4:5] op_sel_hi:[1,0]
	v_mul_f32_e32 v4, v11, v11
	v_pk_fma_f32 v[2:3], v[10:11], v[10:11], v[2:3]
	s_waitcnt lgkmcnt(1)
	v_pk_fma_f32 v[6:7], v[14:15], v[78:79], v[86:87] op_sel_hi:[1,0,1] neg_lo:[0,0,1] neg_hi:[0,0,1]
	v_pk_add_f32 v[2:3], v[2:3], v[4:5] op_sel_hi:[1,0]
	v_mul_f32_e32 v4, v9, v9
	v_pk_fma_f32 v[2:3], v[8:9], v[8:9], v[2:3]
	v_mul_f32_e32 v12, v7, v7
	v_pk_add_f32 v[4:5], v[2:3], v[4:5] op_sel_hi:[1,0]
	s_waitcnt lgkmcnt(0)
	v_pk_fma_f32 v[2:3], v[16:17], v[78:79], v[96:97] op_sel_hi:[1,0,1] neg_lo:[0,0,1] neg_hi:[0,0,1]
	v_pk_fma_f32 v[4:5], v[6:7], v[6:7], v[4:5]
	v_add_u32_e32 v24, 8, v66
	v_pk_add_f32 v[4:5], v[4:5], v[12:13] op_sel_hi:[1,0]
	v_mul_f32_e32 v12, v3, v3
	v_pk_fma_f32 v[4:5], v[2:3], v[2:3], v[4:5]
	v_mov_b32_e32 v25, v0
	v_pk_add_f32 v[4:5], v[4:5], v[12:13] op_sel_hi:[1,0]
	v_lshl_add_u64 v[24:25], v[24:25], 1, s[46:47]
	v_mov_b32_e32 v1, v4
	s_nop 1
	v_permlane32_swap_b32_e32 v4, v1
	v_add_f32_e32 v1, v4, v1
	v_mov_b32_e32 v4, 0x3727c5ac
	v_fmamk_f32 v1, v1, 0x3c000000, v4
	v_mul_f32_e32 v4, 0x4b800000, v1
	v_cmp_gt_f32_e32 vcc, s82, v1
	v_mov_b32_e32 v5, v0
	v_add_u32_e32 v30, 16, v72
	v_cndmask_b32_e32 v1, v1, v4, vcc
	v_rsq_f32_e32 v1, v1
	v_add_u32_e32 v4, 8, v72
	v_lshl_add_u64 v[12:13], v[4:5], 1, s[26:27]
	v_mov_b32_e32 v31, v0
	v_mul_f32_e32 v4, 0x45800000, v1
	v_cndmask_b32_e32 v1, v1, v4, vcc
	v_mul_f32_e32 v4, s2, v1
	v_pk_mul_f32 v[14:15], v[88:89], v[4:5] op_sel_hi:[1,0]
	v_pk_mul_f32 v[16:17], v[80:81], v[4:5] op_sel_hi:[1,0]
	s_waitcnt vmcnt(0)
; __device__ __forceinline__ unsigned pk_bf16(float lo, float hi) { const f32x2 v = {lo, hi}; const bf16v2 b = __builtin_convertvector(v, bf16v2); return __builtin_bit_cast(unsigned, b); }
; __device__ __forceinline__ float bf_lo(unsigned u) { return __uint_as_float(u << 16); }
; __device__ __forceinline__ float bf_hi(unsigned u) { return __uint_as_float(u & 0xffff0000u); }
; __device__ __forceinline__ float silu_f(float v) { return v * __builtin_amdgcn_rcpf(1.0f + __builtin_amdgcn_exp2f(-LOG2E * v)); }
; __device__ __forceinline__ void diff_attn_phase(const Params& p, LAS unsigned char* lds) {
;     ...
;                     for (int i4 = 0; i4 < 4; ++i4) { const int dvc = 32 * t + 8 * i4, dv = dvc + 4 * hhe; const u32x2 z = *(const u32x2*)(zp + (zo + dvc)); const f32x4 sg = *(const f32x4*)(p.diff_subln_g + dv);
;                         u32x2 wv; wv.x = pk_bf16(O[r][t][4 * i4] * rn * sg[0] * silu_f(bf_lo(z.x)), O[r][t][4 * i4 + 1] * rn * sg[1] * silu_f(bf_hi(z.x)));
;                         wv.y = pk_bf16(O[r][t][4 * i4 + 2] * rn * sg[2] * silu_f(bf_lo(z.y)), O[r][t][4 * i4 + 3] * rn * sg[3] * silu_f(bf_hi(z.y)));
;                         *(u32x2*)(Y + h * 128 + (yo + dvc)) = wv; if (i4 == 3) __builtin_amdgcn_sched_barrier(0); }
	v_pk_mul_f32 v[14:15], v[34:35], v[14:15]
	v_pk_mul_f32 v[16:17], v[36:37], v[16:17]
	v_pk_mul_f32 v[14:15], v[64:65], v[14:15]
	v_pk_mul_f32 v[16:17], v[128:129], v[16:17]
	v_cvt_pk_bf16_f32 v14, v14, v15
	v_cvt_pk_bf16_f32 v15, v16, v17
	global_store_dwordx2 v[46:47], v[14:15], off
	global_load_dwordx2 v[66:67], v[12:13], off
	global_load_dwordx4 v[96:99], v[68:69], off offset:32
	global_load_dwordx2 v[72:73], v[12:13], off offset:16
	global_load_dwordx4 v[104:107], v[68:69], off offset:64
	global_load_dwordx2 v[78:79], v[12:13], off offset:32
	global_load_dwordx4 v[108:111], v[68:69], off offset:96
	global_load_dwordx2 v[80:81], v[12:13], off offset:48
	global_load_dwordx4 v[112:115], v[68:69], off offset:128
	global_load_dwordx2 v[86:87], v[12:13], off offset:64
	global_load_dwordx4 v[116:119], v[68:69], off offset:160
	global_load_dwordx2 v[88:89], v[12:13], off offset:80
	global_load_dwordx4 v[120:123], v[68:69], off offset:192
	global_load_dwordx2 v[102:103], v[12:13], off offset:96
	global_load_dwordx4 v[124:127], v[68:69], off offset:224
	global_load_dwordx2 v[132:133], v[12:13], off offset:112
	global_load_dwordx4 v[128:131], v[68:69], off offset:256
	global_load_dwordx2 v[134:135], v[12:13], off offset:128
	global_load_dwordx4 v[136:139], v[68:69], off offset:288
	global_load_dwordx2 v[144:145], v[12:13], off offset:144
	global_load_dwordx4 v[140:143], v[68:69], off offset:320
	global_load_dwordx2 v[146:147], v[12:13], off offset:160
	global_load_dwordx4 v[148:151], v[68:69], off offset:352
	global_load_dwordx2 v[156:157], v[12:13], off offset:176
	global_load_dwordx4 v[152:155], v[68:69], off offset:384
	global_load_dwordx2 v[158:159], v[12:13], off offset:192
	global_load_dwordx4 v[168:171], v[68:69], off offset:416
	global_load_dwordx2 v[160:161], v[12:13], off offset:208
	global_load_dwordx4 v[172:175], v[68:69], off offset:448
	global_load_dwordx2 v[166:167], v[12:13], off offset:224
	global_load_dwordx4 v[176:179], v[68:69], off offset:480
	s_waitcnt vmcnt(28)
	v_lshlrev_b32_e32 v14, 16, v66
	v_and_b32_e32 v15, 0xffff0000, v66
	v_lshlrev_b32_e32 v16, 16, v67
	v_and_b32_e32 v17, 0xffff0000, v67
	v_mul_f32_e32 v24, 0xbfb8aa3b, v14
	v_mul_f32_e32 v25, 0xbfb8aa3b, v15
	v_mul_f32_e32 v30, 0xbfb8aa3b, v16
	v_mul_f32_e32 v31, 0xbfb8aa3b, v17
	v_exp_f32_e32 v24, v24
	v_exp_f32_e32 v25, v25
	v_exp_f32_e32 v30, v30
	v_exp_f32_e32 v31, v31
	v_add_f32_e32 v24, 1.0, v24
	v_add_f32_e32 v25, 1.0, v25
	v_add_f32_e32 v30, 1.0, v30
	v_add_f32_e32 v31, 1.0, v31
	v_rcp_f32_e32 v24, v24
	v_rcp_f32_e32 v25, v25
	v_rcp_f32_e32 v30, v30
	v_rcp_f32_e32 v31, v31
	v_pk_mul_f32 v[32:33], v[100:101], v[4:5] op_sel_hi:[1,0]
	v_pk_mul_f32 v[34:35], v[56:57], v[4:5] op_sel_hi:[1,0]
	v_pk_mul_f32 v[32:33], v[96:97], v[32:33]
	v_pk_mul_f32 v[34:35], v[98:99], v[34:35]
	v_pk_mul_f32 v[14:15], v[24:25], v[14:15]
	v_pk_mul_f32 v[16:17], v[30:31], v[16:17]
	v_pk_mul_f32 v[32:33], v[32:33], v[14:15]
	v_pk_mul_f32 v[34:35], v[34:35], v[16:17]
	v_cvt_pk_bf16_f32 v36, v32, v33
	v_cvt_pk_bf16_f32 v37, v34, v35
	global_store_dwordx2 v[46:47], v[36:37], off offset:16
	s_waitcnt vmcnt(27)
	v_lshlrev_b32_e32 v14, 16, v72
	v_and_b32_e32 v15, 0xffff0000, v72
	v_lshlrev_b32_e32 v16, 16, v73
	v_and_b32_e32 v17, 0xffff0000, v73
	v_mul_f32_e32 v24, 0xbfb8aa3b, v14
	v_mul_f32_e32 v25, 0xbfb8aa3b, v15
	v_mul_f32_e32 v30, 0xbfb8aa3b, v16
	v_mul_f32_e32 v31, 0xbfb8aa3b, v17
	v_exp_f32_e32 v24, v24
	v_exp_f32_e32 v25, v25
	v_exp_f32_e32 v30, v30
	v_exp_f32_e32 v31, v31
	v_add_f32_e32 v24, 1.0, v24
	v_add_f32_e32 v25, 1.0, v25
	v_add_f32_e32 v30, 1.0, v30
	v_add_f32_e32 v31, 1.0, v31
	v_rcp_f32_e32 v24, v24
	v_rcp_f32_e32 v25, v25
	v_rcp_f32_e32 v30, v30
	v_rcp_f32_e32 v31, v31
	v_pk_mul_f32 v[32:33], v[58:59], v[4:5] op_sel_hi:[1,0]
	v_pk_mul_f32 v[34:35], v[50:51], v[4:5] op_sel_hi:[1,0]
	v_pk_mul_f32 v[32:33], v[104:105], v[32:33]
	v_pk_mul_f32 v[34:35], v[106:107], v[34:35]
	v_pk_mul_f32 v[14:15], v[24:25], v[14:15]
	v_pk_mul_f32 v[16:17], v[30:31], v[16:17]
	v_pk_mul_f32 v[32:33], v[32:33], v[14:15]
	v_pk_mul_f32 v[34:35], v[34:35], v[16:17]
	v_cvt_pk_bf16_f32 v64, v32, v33
	v_cvt_pk_bf16_f32 v65, v34, v35
	global_store_dwordx2 v[46:47], v[64:65], off offset:32
	s_waitcnt vmcnt(26)
	v_lshlrev_b32_e32 v14, 16, v78
	v_and_b32_e32 v15, 0xffff0000, v78
	v_lshlrev_b32_e32 v16, 16, v79
	v_and_b32_e32 v17, 0xffff0000, v79
	v_mul_f32_e32 v24, 0xbfb8aa3b, v14
	v_mul_f32_e32 v25, 0xbfb8aa3b, v15
	v_mul_f32_e32 v30, 0xbfb8aa3b, v16
	v_mul_f32_e32 v31, 0xbfb8aa3b, v17
	v_exp_f32_e32 v24, v24
	v_exp_f32_e32 v25, v25
	v_exp_f32_e32 v30, v30
	v_exp_f32_e32 v31, v31
	v_add_f32_e32 v24, 1.0, v24
	v_add_f32_e32 v25, 1.0, v25
	v_add_f32_e32 v30, 1.0, v30
	v_add_f32_e32 v31, 1.0, v31
	v_rcp_f32_e32 v24, v24
	v_rcp_f32_e32 v25, v25
	v_rcp_f32_e32 v30, v30
	v_rcp_f32_e32 v31, v31
	v_pk_mul_f32 v[32:33], v[94:95], v[4:5] op_sel_hi:[1,0]
	v_pk_mul_f32 v[34:35], v[92:93], v[4:5] op_sel_hi:[1,0]
	v_pk_mul_f32 v[32:33], v[108:109], v[32:33]
	v_pk_mul_f32 v[34:35], v[110:111], v[34:35]
	v_pk_mul_f32 v[14:15], v[24:25], v[14:15]
	v_pk_mul_f32 v[16:17], v[30:31], v[16:17]
	v_pk_mul_f32 v[32:33], v[32:33], v[14:15]
	v_pk_mul_f32 v[34:35], v[34:35], v[16:17]
	v_cvt_pk_bf16_f32 v36, v32, v33
	v_cvt_pk_bf16_f32 v37, v34, v35
	global_store_dwordx2 v[46:47], v[36:37], off offset:48
	s_waitcnt vmcnt(25)
; __device__ __forceinline__ unsigned pk_bf16(float lo, float hi) { const f32x2 v = {lo, hi}; const bf16v2 b = __builtin_convertvector(v, bf16v2); return __builtin_bit_cast(unsigned, b); }
; __device__ __forceinline__ float bf_lo(unsigned u) { return __uint_as_float(u << 16); }
; __device__ __forceinline__ float bf_hi(unsigned u) { return __uint_as_float(u & 0xffff0000u); }
; __device__ __forceinline__ float silu_f(float v) { return v * __builtin_amdgcn_rcpf(1.0f + __builtin_amdgcn_exp2f(-LOG2E * v)); }
; __device__ __forceinline__ void diff_attn_phase(const Params& p, LAS unsigned char* lds) {
;     ...
;                     for (int i4 = 0; i4 < 4; ++i4) { const int dvc = 32 * t + 8 * i4, dv = dvc + 4 * hhe; const u32x2 z = *(const u32x2*)(zp + (zo + dvc)); const f32x4 sg = *(const f32x4*)(p.diff_subln_g + dv);
;                         u32x2 wv; wv.x = pk_bf16(O[r][t][4 * i4] * rn * sg[0] * silu_f(bf_lo(z.x)), O[r][t][4 * i4 + 1] * rn * sg[1] * silu_f(bf_hi(z.x)));
;                         wv.y = pk_bf16(O[r][t][4 * i4 + 2] * rn * sg[2] * silu_f(bf_lo(z.y)), O[r][t][4 * i4 + 3] * rn * sg[3] * silu_f(bf_hi(z.y)));
;                         *(u32x2*)(Y + h * 128 + (yo + dvc)) = wv; if (i4 == 3) __builtin_amdgcn_sched_barrier(0); }
	v_lshlrev_b32_e32 v14, 16, v80
	v_and_b32_e32 v15, 0xffff0000, v80
	v_lshlrev_b32_e32 v16, 16, v81
	v_and_b32_e32 v17, 0xffff0000, v81
	v_mul_f32_e32 v24, 0xbfb8aa3b, v14
	v_mul_f32_e32 v25, 0xbfb8aa3b, v15
	v_mul_f32_e32 v30, 0xbfb8aa3b, v16
	v_mul_f32_e32 v31, 0xbfb8aa3b, v17
	v_exp_f32_e32 v24, v24
	v_exp_f32_e32 v25, v25
	v_exp_f32_e32 v30, v30
	v_exp_f32_e32 v31, v31
	v_add_f32_e32 v24, 1.0, v24
	v_add_f32_e32 v25, 1.0, v25
	v_add_f32_e32 v30, 1.0, v30
	v_add_f32_e32 v31, 1.0, v31
	v_rcp_f32_e32 v24, v24
	v_rcp_f32_e32 v25, v25
	v_rcp_f32_e32 v30, v30
	v_rcp_f32_e32 v31, v31
	v_pk_mul_f32 v[32:33], v[90:91], v[4:5] op_sel_hi:[1,0]
	v_pk_mul_f32 v[34:35], v[84:85], v[4:5] op_sel_hi:[1,0]
	v_pk_mul_f32 v[32:33], v[112:113], v[32:33]
	v_pk_mul_f32 v[34:35], v[114:115], v[34:35]
	v_pk_mul_f32 v[14:15], v[24:25], v[14:15]
	v_pk_mul_f32 v[16:17], v[30:31], v[16:17]
	v_pk_mul_f32 v[32:33], v[32:33], v[14:15]
	v_pk_mul_f32 v[34:35], v[34:35], v[16:17]
	v_cvt_pk_bf16_f32 v64, v32, v33
	v_cvt_pk_bf16_f32 v65, v34, v35
	global_store_dwordx2 v[46:47], v[64:65], off offset:64
	s_waitcnt vmcnt(24)
	v_lshlrev_b32_e32 v14, 16, v86
	v_and_b32_e32 v15, 0xffff0000, v86
	v_lshlrev_b32_e32 v16, 16, v87
	v_and_b32_e32 v17, 0xffff0000, v87
	v_mul_f32_e32 v24, 0xbfb8aa3b, v14
	v_mul_f32_e32 v25, 0xbfb8aa3b, v15
	v_mul_f32_e32 v30, 0xbfb8aa3b, v16
	v_mul_f32_e32 v31, 0xbfb8aa3b, v17
	v_exp_f32_e32 v24, v24
	v_exp_f32_e32 v25, v25
	v_exp_f32_e32 v30, v30
	v_exp_f32_e32 v31, v31
	v_add_f32_e32 v24, 1.0, v24
	v_add_f32_e32 v25, 1.0, v25
	v_add_f32_e32 v30, 1.0, v30
	v_add_f32_e32 v31, 1.0, v31
	v_rcp_f32_e32 v24, v24
	v_rcp_f32_e32 v25, v25
	v_rcp_f32_e32 v30, v30
	v_rcp_f32_e32 v31, v31
	v_pk_mul_f32 v[32:33], v[82:83], v[4:5] op_sel_hi:[1,0]
	v_pk_mul_f32 v[34:35], v[76:77], v[4:5] op_sel_hi:[1,0]
	v_pk_mul_f32 v[32:33], v[116:117], v[32:33]
	v_pk_mul_f32 v[34:35], v[118:119], v[34:35]
	v_pk_mul_f32 v[14:15], v[24:25], v[14:15]
	v_pk_mul_f32 v[16:17], v[30:31], v[16:17]
	v_pk_mul_f32 v[32:33], v[32:33], v[14:15]
	v_pk_mul_f32 v[34:35], v[34:35], v[16:17]
	v_cvt_pk_bf16_f32 v36, v32, v33
	v_cvt_pk_bf16_f32 v37, v34, v35
	global_store_dwordx2 v[46:47], v[36:37], off offset:80
	s_waitcnt vmcnt(23)
	v_lshlrev_b32_e32 v14, 16, v88
	v_and_b32_e32 v15, 0xffff0000, v88
	v_lshlrev_b32_e32 v16, 16, v89
	v_and_b32_e32 v17, 0xffff0000, v89
	v_mul_f32_e32 v24, 0xbfb8aa3b, v14
	v_mul_f32_e32 v25, 0xbfb8aa3b, v15
	v_mul_f32_e32 v30, 0xbfb8aa3b, v16
	v_mul_f32_e32 v31, 0xbfb8aa3b, v17
	v_exp_f32_e32 v24, v24
	v_exp_f32_e32 v25, v25
	v_exp_f32_e32 v30, v30
	v_exp_f32_e32 v31, v31
	v_add_f32_e32 v24, 1.0, v24
	v_add_f32_e32 v25, 1.0, v25
	v_add_f32_e32 v30, 1.0, v30
	v_add_f32_e32 v31, 1.0, v31
	v_rcp_f32_e32 v24, v24
	v_rcp_f32_e32 v25, v25
	v_rcp_f32_e32 v30, v30
	v_rcp_f32_e32 v31, v31
	v_pk_mul_f32 v[32:33], v[74:75], v[4:5] op_sel_hi:[1,0]
	v_pk_mul_f32 v[34:35], v[70:71], v[4:5] op_sel_hi:[1,0]
	v_pk_mul_f32 v[32:33], v[120:121], v[32:33]
	v_pk_mul_f32 v[34:35], v[122:123], v[34:35]
	v_pk_mul_f32 v[14:15], v[24:25], v[14:15]
	v_pk_mul_f32 v[16:17], v[30:31], v[16:17]
	v_pk_mul_f32 v[32:33], v[32:33], v[14:15]
	v_pk_mul_f32 v[34:35], v[34:35], v[16:17]
	v_cvt_pk_bf16_f32 v64, v32, v33
	v_cvt_pk_bf16_f32 v65, v34, v35
	global_store_dwordx2 v[46:47], v[64:65], off offset:96
	s_waitcnt vmcnt(22)
	v_lshlrev_b32_e32 v14, 16, v102
	v_and_b32_e32 v15, 0xffff0000, v102
	v_lshlrev_b32_e32 v16, 16, v103
	v_and_b32_e32 v17, 0xffff0000, v103
	v_mul_f32_e32 v24, 0xbfb8aa3b, v14
	v_mul_f32_e32 v25, 0xbfb8aa3b, v15
	v_mul_f32_e32 v30, 0xbfb8aa3b, v16
	v_mul_f32_e32 v31, 0xbfb8aa3b, v17
	v_exp_f32_e32 v24, v24
	v_exp_f32_e32 v25, v25
	v_exp_f32_e32 v30, v30
	v_exp_f32_e32 v31, v31
	v_add_f32_e32 v24, 1.0, v24
	v_add_f32_e32 v25, 1.0, v25
	v_add_f32_e32 v30, 1.0, v30
	v_add_f32_e32 v31, 1.0, v31
	v_rcp_f32_e32 v24, v24
	v_rcp_f32_e32 v25, v25
	v_rcp_f32_e32 v30, v30
	v_rcp_f32_e32 v31, v31
	v_pk_mul_f32 v[32:33], v[62:63], v[4:5] op_sel_hi:[1,0]
	v_pk_mul_f32 v[34:35], v[60:61], v[4:5] op_sel_hi:[1,0]
	v_pk_mul_f32 v[32:33], v[124:125], v[32:33]
	v_pk_mul_f32 v[34:35], v[126:127], v[34:35]
	v_pk_mul_f32 v[14:15], v[24:25], v[14:15]
	v_pk_mul_f32 v[16:17], v[30:31], v[16:17]
	v_pk_mul_f32 v[32:33], v[32:33], v[14:15]
	v_pk_mul_f32 v[34:35], v[34:35], v[16:17]
	v_cvt_pk_bf16_f32 v36, v32, v33
	v_cvt_pk_bf16_f32 v37, v34, v35
	global_store_dwordx2 v[46:47], v[36:37], off offset:112
	s_waitcnt vmcnt(21)
	v_lshlrev_b32_e32 v14, 16, v132
	v_and_b32_e32 v15, 0xffff0000, v132
	v_lshlrev_b32_e32 v16, 16, v133
	v_and_b32_e32 v17, 0xffff0000, v133
	v_mul_f32_e32 v24, 0xbfb8aa3b, v14
	v_mul_f32_e32 v25, 0xbfb8aa3b, v15
	v_mul_f32_e32 v30, 0xbfb8aa3b, v16
	v_mul_f32_e32 v31, 0xbfb8aa3b, v17
	v_exp_f32_e32 v24, v24
	v_exp_f32_e32 v25, v25
	v_exp_f32_e32 v30, v30
	v_exp_f32_e32 v31, v31
	v_add_f32_e32 v24, 1.0, v24
	v_add_f32_e32 v25, 1.0, v25
	v_add_f32_e32 v30, 1.0, v30
	v_add_f32_e32 v31, 1.0, v31
	v_rcp_f32_e32 v24, v24
	v_rcp_f32_e32 v25, v25
	v_rcp_f32_e32 v30, v30
	v_rcp_f32_e32 v31, v31
	v_pk_mul_f32 v[32:33], v[54:55], v[4:5] op_sel_hi:[1,0]
	v_pk_mul_f32 v[34:35], v[52:53], v[4:5] op_sel_hi:[1,0]
	v_pk_mul_f32 v[32:33], v[128:129], v[32:33]
	v_pk_mul_f32 v[34:35], v[130:131], v[34:35]
	v_pk_mul_f32 v[14:15], v[24:25], v[14:15]
	v_pk_mul_f32 v[16:17], v[30:31], v[16:17]
	v_pk_mul_f32 v[32:33], v[32:33], v[14:15]
	v_pk_mul_f32 v[34:35], v[34:35], v[16:17]
	v_cvt_pk_bf16_f32 v64, v32, v33
	v_cvt_pk_bf16_f32 v65, v34, v35
	global_store_dwordx2 v[46:47], v[64:65], off offset:128
	s_waitcnt vmcnt(20)
; __device__ __forceinline__ unsigned pk_bf16(float lo, float hi) { const f32x2 v = {lo, hi}; const bf16v2 b = __builtin_convertvector(v, bf16v2); return __builtin_bit_cast(unsigned, b); }
; __device__ __forceinline__ float bf_lo(unsigned u) { return __uint_as_float(u << 16); }
; __device__ __forceinline__ float bf_hi(unsigned u) { return __uint_as_float(u & 0xffff0000u); }
; __device__ __forceinline__ float silu_f(float v) { return v * __builtin_amdgcn_rcpf(1.0f + __builtin_amdgcn_exp2f(-LOG2E * v)); }
; __device__ __forceinline__ void diff_attn_phase(const Params& p, LAS unsigned char* lds) {
;     ...
;                     for (int i4 = 0; i4 < 4; ++i4) { const int dvc = 32 * t + 8 * i4, dv = dvc + 4 * hhe; const u32x2 z = *(const u32x2*)(zp + (zo + dvc)); const f32x4 sg = *(const f32x4*)(p.diff_subln_g + dv);
;                         u32x2 wv; wv.x = pk_bf16(O[r][t][4 * i4] * rn * sg[0] * silu_f(bf_lo(z.x)), O[r][t][4 * i4 + 1] * rn * sg[1] * silu_f(bf_hi(z.x)));
;                         wv.y = pk_bf16(O[r][t][4 * i4 + 2] * rn * sg[2] * silu_f(bf_lo(z.y)), O[r][t][4 * i4 + 3] * rn * sg[3] * silu_f(bf_hi(z.y)));
;                         *(u32x2*)(Y + h * 128 + (yo + dvc)) = wv; if (i4 == 3) __builtin_amdgcn_sched_barrier(0); }
	v_lshlrev_b32_e32 v14, 16, v134
	v_and_b32_e32 v15, 0xffff0000, v134
	v_lshlrev_b32_e32 v16, 16, v135
	v_and_b32_e32 v17, 0xffff0000, v135
	v_mul_f32_e32 v24, 0xbfb8aa3b, v14
	v_mul_f32_e32 v25, 0xbfb8aa3b, v15
	v_mul_f32_e32 v30, 0xbfb8aa3b, v16
	v_mul_f32_e32 v31, 0xbfb8aa3b, v17
	v_exp_f32_e32 v24, v24
	v_exp_f32_e32 v25, v25
	v_exp_f32_e32 v30, v30
	v_exp_f32_e32 v31, v31
	v_add_f32_e32 v24, 1.0, v24
	v_add_f32_e32 v25, 1.0, v25
	v_add_f32_e32 v30, 1.0, v30
	v_add_f32_e32 v31, 1.0, v31
	v_rcp_f32_e32 v24, v24
	v_rcp_f32_e32 v25, v25
	v_rcp_f32_e32 v30, v30
	v_rcp_f32_e32 v31, v31
	v_pk_mul_f32 v[32:33], v[48:49], v[4:5] op_sel_hi:[1,0]
	v_pk_mul_f32 v[34:35], v[44:45], v[4:5] op_sel_hi:[1,0]
	v_pk_mul_f32 v[32:33], v[136:137], v[32:33]
	v_pk_mul_f32 v[34:35], v[138:139], v[34:35]
	v_pk_mul_f32 v[14:15], v[24:25], v[14:15]
	v_pk_mul_f32 v[16:17], v[30:31], v[16:17]
	v_pk_mul_f32 v[32:33], v[32:33], v[14:15]
	v_pk_mul_f32 v[34:35], v[34:35], v[16:17]
	v_cvt_pk_bf16_f32 v36, v32, v33
	v_cvt_pk_bf16_f32 v37, v34, v35
	global_store_dwordx2 v[46:47], v[36:37], off offset:144
	s_waitcnt vmcnt(19)
	v_lshlrev_b32_e32 v14, 16, v144
	v_and_b32_e32 v15, 0xffff0000, v144
	v_lshlrev_b32_e32 v16, 16, v145
	v_and_b32_e32 v17, 0xffff0000, v145
	v_mul_f32_e32 v24, 0xbfb8aa3b, v14
	v_mul_f32_e32 v25, 0xbfb8aa3b, v15
	v_mul_f32_e32 v30, 0xbfb8aa3b, v16
	v_mul_f32_e32 v31, 0xbfb8aa3b, v17
	v_exp_f32_e32 v24, v24
	v_exp_f32_e32 v25, v25
	v_exp_f32_e32 v30, v30
	v_exp_f32_e32 v31, v31
	v_add_f32_e32 v24, 1.0, v24
	v_add_f32_e32 v25, 1.0, v25
	v_add_f32_e32 v30, 1.0, v30
	v_add_f32_e32 v31, 1.0, v31
	v_rcp_f32_e32 v24, v24
	v_rcp_f32_e32 v25, v25
	v_rcp_f32_e32 v30, v30
	v_rcp_f32_e32 v31, v31
	v_pk_mul_f32 v[32:33], v[42:43], v[4:5] op_sel_hi:[1,0]
	v_pk_mul_f32 v[34:35], v[40:41], v[4:5] op_sel_hi:[1,0]
	v_pk_mul_f32 v[32:33], v[140:141], v[32:33]
	v_pk_mul_f32 v[34:35], v[142:143], v[34:35]
	v_pk_mul_f32 v[14:15], v[24:25], v[14:15]
	v_pk_mul_f32 v[16:17], v[30:31], v[16:17]
	v_pk_mul_f32 v[32:33], v[32:33], v[14:15]
	v_pk_mul_f32 v[34:35], v[34:35], v[16:17]
	v_cvt_pk_bf16_f32 v64, v32, v33
	v_cvt_pk_bf16_f32 v65, v34, v35
	global_store_dwordx2 v[46:47], v[64:65], off offset:160
	s_waitcnt vmcnt(18)
	v_lshlrev_b32_e32 v14, 16, v146
	v_and_b32_e32 v15, 0xffff0000, v146
	v_lshlrev_b32_e32 v16, 16, v147
	v_and_b32_e32 v17, 0xffff0000, v147
	v_mul_f32_e32 v24, 0xbfb8aa3b, v14
	v_mul_f32_e32 v25, 0xbfb8aa3b, v15
	v_mul_f32_e32 v30, 0xbfb8aa3b, v16
	v_mul_f32_e32 v31, 0xbfb8aa3b, v17
	v_exp_f32_e32 v24, v24
	v_exp_f32_e32 v25, v25
	v_exp_f32_e32 v30, v30
	v_exp_f32_e32 v31, v31
	v_add_f32_e32 v24, 1.0, v24
	v_add_f32_e32 v25, 1.0, v25
	v_add_f32_e32 v30, 1.0, v30
	v_add_f32_e32 v31, 1.0, v31
	v_rcp_f32_e32 v24, v24
	v_rcp_f32_e32 v25, v25
	v_rcp_f32_e32 v30, v30
	v_rcp_f32_e32 v31, v31
	v_pk_mul_f32 v[32:33], v[38:39], v[4:5] op_sel_hi:[1,0]
	v_pk_mul_f32 v[34:35], v[28:29], v[4:5] op_sel_hi:[1,0]
	v_pk_mul_f32 v[32:33], v[148:149], v[32:33]
	v_pk_mul_f32 v[34:35], v[150:151], v[34:35]
	v_pk_mul_f32 v[14:15], v[24:25], v[14:15]
	v_pk_mul_f32 v[16:17], v[30:31], v[16:17]
	v_pk_mul_f32 v[32:33], v[32:33], v[14:15]
	v_pk_mul_f32 v[34:35], v[34:35], v[16:17]
	v_cvt_pk_bf16_f32 v36, v32, v33
	v_cvt_pk_bf16_f32 v37, v34, v35
	global_store_dwordx2 v[46:47], v[36:37], off offset:176
	s_waitcnt vmcnt(17)
; __device__ __forceinline__ unsigned pk_bf16(float lo, float hi) { const f32x2 v = {lo, hi}; const bf16v2 b = __builtin_convertvector(v, bf16v2); return __builtin_bit_cast(unsigned, b); }
; __device__ __forceinline__ float bf_lo(unsigned u) { return __uint_as_float(u << 16); }
; __device__ __forceinline__ float bf_hi(unsigned u) { return __uint_as_float(u & 0xffff0000u); }
; __device__ __forceinline__ float silu_f(float v) { return v * __builtin_amdgcn_rcpf(1.0f + __builtin_amdgcn_exp2f(-LOG2E * v)); }
; __device__ __forceinline__ void diff_attn_phase(const Params& p, LAS unsigned char* lds) {
;     ...
;                     for (int i4 = 0; i4 < 4; ++i4) { const int dvc = 32 * t + 8 * i4, dv = dvc + 4 * hhe; const u32x2 z = *(const u32x2*)(zp + (zo + dvc)); const f32x4 sg = *(const f32x4*)(p.diff_subln_g + dv);
;                         u32x2 wv; wv.x = pk_bf16(O[r][t][4 * i4] * rn * sg[0] * silu_f(bf_lo(z.x)), O[r][t][4 * i4 + 1] * rn * sg[1] * silu_f(bf_hi(z.x)));
;                         wv.y = pk_bf16(O[r][t][4 * i4 + 2] * rn * sg[2] * silu_f(bf_lo(z.y)), O[r][t][4 * i4 + 3] * rn * sg[3] * silu_f(bf_hi(z.y)));
;                         *(u32x2*)(Y + h * 128 + (yo + dvc)) = wv; if (i4 == 3) __builtin_amdgcn_sched_barrier(0); }
	v_lshlrev_b32_e32 v14, 16, v156
	v_and_b32_e32 v15, 0xffff0000, v156
	v_lshlrev_b32_e32 v16, 16, v157
	v_and_b32_e32 v17, 0xffff0000, v157
	v_mul_f32_e32 v24, 0xbfb8aa3b, v14
	v_mul_f32_e32 v25, 0xbfb8aa3b, v15
	v_mul_f32_e32 v30, 0xbfb8aa3b, v16
	v_mul_f32_e32 v31, 0xbfb8aa3b, v17
	v_exp_f32_e32 v24, v24
	v_exp_f32_e32 v25, v25
	v_exp_f32_e32 v30, v30
	v_exp_f32_e32 v31, v31
	v_add_f32_e32 v24, 1.0, v24
	v_add_f32_e32 v25, 1.0, v25
	v_add_f32_e32 v30, 1.0, v30
	v_add_f32_e32 v31, 1.0, v31
	v_rcp_f32_e32 v24, v24
	v_rcp_f32_e32 v25, v25
	v_rcp_f32_e32 v30, v30
	v_rcp_f32_e32 v31, v31
	v_pk_mul_f32 v[32:33], v[26:27], v[4:5] op_sel_hi:[1,0]
	v_pk_mul_f32 v[34:35], v[22:23], v[4:5] op_sel_hi:[1,0]
	v_pk_mul_f32 v[32:33], v[152:153], v[32:33]
	v_pk_mul_f32 v[34:35], v[154:155], v[34:35]
	v_pk_mul_f32 v[14:15], v[24:25], v[14:15]
	v_pk_mul_f32 v[16:17], v[30:31], v[16:17]
	v_pk_mul_f32 v[32:33], v[32:33], v[14:15]
	v_pk_mul_f32 v[34:35], v[34:35], v[16:17]
	v_cvt_pk_bf16_f32 v64, v32, v33
	v_cvt_pk_bf16_f32 v65, v34, v35
	global_store_dwordx2 v[46:47], v[64:65], off offset:192
	s_waitcnt vmcnt(16)
	v_lshlrev_b32_e32 v14, 16, v158
	v_and_b32_e32 v15, 0xffff0000, v158
	v_lshlrev_b32_e32 v16, 16, v159
	v_and_b32_e32 v17, 0xffff0000, v159
	v_mul_f32_e32 v24, 0xbfb8aa3b, v14
	v_mul_f32_e32 v25, 0xbfb8aa3b, v15
	v_mul_f32_e32 v30, 0xbfb8aa3b, v16
	v_mul_f32_e32 v31, 0xbfb8aa3b, v17
	v_exp_f32_e32 v24, v24
	v_exp_f32_e32 v25, v25
	v_exp_f32_e32 v30, v30
	v_exp_f32_e32 v31, v31
	v_add_f32_e32 v24, 1.0, v24
	v_add_f32_e32 v25, 1.0, v25
	v_add_f32_e32 v30, 1.0, v30
	v_add_f32_e32 v31, 1.0, v31
	v_rcp_f32_e32 v24, v24
	v_rcp_f32_e32 v25, v25
	v_rcp_f32_e32 v30, v30
	v_rcp_f32_e32 v31, v31
	v_pk_mul_f32 v[32:33], v[20:21], v[4:5] op_sel_hi:[1,0]
	v_pk_mul_f32 v[34:35], v[18:19], v[4:5] op_sel_hi:[1,0]
	v_pk_mul_f32 v[32:33], v[168:169], v[32:33]
	v_pk_mul_f32 v[34:35], v[170:171], v[34:35]
	v_pk_mul_f32 v[14:15], v[24:25], v[14:15]
	v_pk_mul_f32 v[16:17], v[30:31], v[16:17]
	v_pk_mul_f32 v[32:33], v[32:33], v[14:15]
	v_pk_mul_f32 v[34:35], v[34:35], v[16:17]
	v_cvt_pk_bf16_f32 v36, v32, v33
	v_cvt_pk_bf16_f32 v37, v34, v35
	global_store_dwordx2 v[46:47], v[36:37], off offset:208
	s_waitcnt vmcnt(15)
	v_lshlrev_b32_e32 v14, 16, v160
	v_and_b32_e32 v15, 0xffff0000, v160
	v_lshlrev_b32_e32 v16, 16, v161
	v_and_b32_e32 v17, 0xffff0000, v161
	v_mul_f32_e32 v24, 0xbfb8aa3b, v14
	v_mul_f32_e32 v25, 0xbfb8aa3b, v15
	v_mul_f32_e32 v30, 0xbfb8aa3b, v16
	v_mul_f32_e32 v31, 0xbfb8aa3b, v17
	v_exp_f32_e32 v24, v24
	v_exp_f32_e32 v25, v25
	v_exp_f32_e32 v30, v30
	v_exp_f32_e32 v31, v31
	v_add_f32_e32 v24, 1.0, v24
	v_add_f32_e32 v25, 1.0, v25
	v_add_f32_e32 v30, 1.0, v30
	v_add_f32_e32 v31, 1.0, v31
	v_rcp_f32_e32 v24, v24
	v_rcp_f32_e32 v25, v25
	v_rcp_f32_e32 v30, v30
	v_rcp_f32_e32 v31, v31
	v_pk_mul_f32 v[32:33], v[10:11], v[4:5] op_sel_hi:[1,0]
	v_pk_mul_f32 v[34:35], v[8:9], v[4:5] op_sel_hi:[1,0]
	v_pk_mul_f32 v[32:33], v[172:173], v[32:33]
	v_pk_mul_f32 v[34:35], v[174:175], v[34:35]
	v_pk_mul_f32 v[14:15], v[24:25], v[14:15]
	v_pk_mul_f32 v[16:17], v[30:31], v[16:17]
	v_pk_mul_f32 v[32:33], v[32:33], v[14:15]
	v_pk_mul_f32 v[34:35], v[34:35], v[16:17]
	v_cvt_pk_bf16_f32 v64, v32, v33
	v_cvt_pk_bf16_f32 v65, v34, v35
	global_store_dwordx2 v[46:47], v[64:65], off offset:224
	s_waitcnt vmcnt(14)
	v_lshlrev_b32_e32 v14, 16, v166
	v_and_b32_e32 v15, 0xffff0000, v166
	v_lshlrev_b32_e32 v16, 16, v167
	v_and_b32_e32 v17, 0xffff0000, v167
	v_mul_f32_e32 v24, 0xbfb8aa3b, v14
	v_mul_f32_e32 v25, 0xbfb8aa3b, v15
	v_mul_f32_e32 v30, 0xbfb8aa3b, v16
	v_mul_f32_e32 v31, 0xbfb8aa3b, v17
	v_exp_f32_e32 v24, v24
	v_exp_f32_e32 v25, v25
	v_exp_f32_e32 v30, v30
	v_exp_f32_e32 v31, v31
	v_add_f32_e32 v24, 1.0, v24
	v_add_f32_e32 v25, 1.0, v25
	v_add_f32_e32 v30, 1.0, v30
	v_add_f32_e32 v31, 1.0, v31
	v_rcp_f32_e32 v24, v24
	v_rcp_f32_e32 v25, v25
	v_rcp_f32_e32 v30, v30
	v_rcp_f32_e32 v31, v31
	v_pk_mul_f32 v[32:33], v[6:7], v[4:5] op_sel_hi:[1,0]
	v_pk_mul_f32 v[34:35], v[2:3], v[4:5] op_sel_hi:[1,0]
	v_pk_mul_f32 v[32:33], v[176:177], v[32:33]
	v_pk_mul_f32 v[34:35], v[178:179], v[34:35]
	v_pk_mul_f32 v[14:15], v[24:25], v[14:15]
	v_pk_mul_f32 v[16:17], v[30:31], v[16:17]
	v_pk_mul_f32 v[32:33], v[32:33], v[14:15]
	v_pk_mul_f32 v[34:35], v[34:35], v[16:17]
	v_cvt_pk_bf16_f32 v36, v32, v33
	v_cvt_pk_bf16_f32 v37, v34, v35
	global_store_dwordx2 v[46:47], v[36:37], off offset:240
	s_branch .LBB0_37
